# plus GEMM loops: priority raise before the segment barrier and priority drop after it (off the hand-off path); redundant lgkmcnt(0) dropped
# baseline (speedup 1.0000x reference)
.LBB0_22:
	s_add_u32 s18, s6, 0xfff80080
	s_addc_u32 s19, s7, -1
	s_add_i32 s41, 0, 0x10000
	s_cmp_eq_u32 s40, 28
	s_cselect_b32 s21, s13, s19
	s_cselect_b32 s20, s36, s18
	s_cselect_b32 s19, s11, s39
	s_cselect_b32 s18, s37, s38
	s_add_i32 s44, 0, 0x14000
	v_add_u32_e32 v140, s41, v175
	v_add_u32_e32 v166, s44, v175
	ds_read_b128 v[128:131], v140
	ds_read_b128 v[132:135], v140 offset:1024
	ds_read_b128 v[136:139], v140 offset:2048
	ds_read_b128 v[140:143], v140 offset:3072
	ds_read_b128 v[154:157], v166
	ds_read_b128 v[158:161], v166 offset:1024
	ds_read_b128 v[162:165], v166 offset:2048
	ds_read_b128 v[166:169], v166 offset:3072
	v_lshl_add_u64 v[170:171], s[6:7], 0, v[152:153]
	s_add_i32 m0, s25, 0xc000
	ds_read_b128 v[188:191], v186
	ds_read_b128 v[192:195], v186 offset:1024
	ds_read_b128 v[196:199], v186 offset:2048
	ds_read_b128 v[200:203], v186 offset:3072
	ds_read_b128 v[204:207], v186 offset:4096
	ds_read_b128 v[208:211], v186 offset:5120
	ds_read_b128 v[212:215], v186 offset:6144
	ds_read_b128 v[216:219], v186 offset:7168
	global_load_lds_dwordx4 v[170:171], off
	v_lshl_add_u64 v[170:171], s[6:7], 0, v[150:151]
	s_add_i32 m0, s25, 0xe000
	s_nop 0
	global_load_lds_dwordx4 v[170:171], off
	s_waitcnt vmcnt(8)
	s_waitcnt lgkmcnt(0)
	s_setprio 1
	s_barrier
	v_mfma_f32_16x16x32_bf16 v[124:127], v[128:131], v[188:191], v[124:127]
	v_mfma_f32_16x16x32_bf16 v[116:119], v[136:139], v[188:191], v[116:119]
	v_mfma_f32_16x16x32_bf16 v[108:111], v[128:131], v[196:199], v[108:111]
	v_mfma_f32_16x16x32_bf16 v[100:103], v[136:139], v[196:199], v[100:103]
	v_mfma_f32_16x16x32_bf16 v[92:95], v[128:131], v[204:207], v[92:95]
	v_mfma_f32_16x16x32_bf16 v[84:87], v[136:139], v[204:207], v[84:87]
	v_mfma_f32_16x16x32_bf16 v[76:79], v[128:131], v[212:215], v[76:79]
	v_mfma_f32_16x16x32_bf16 v[68:71], v[136:139], v[212:215], v[68:71]
	v_mfma_f32_16x16x32_bf16 v[124:127], v[132:135], v[192:195], v[124:127]
	v_mfma_f32_16x16x32_bf16 v[116:119], v[140:143], v[192:195], v[116:119]
	v_mfma_f32_16x16x32_bf16 v[108:111], v[132:135], v[200:203], v[108:111]
	v_mfma_f32_16x16x32_bf16 v[100:103], v[140:143], v[200:203], v[100:103]
	v_mfma_f32_16x16x32_bf16 v[92:95], v[132:135], v[208:211], v[92:95]
	v_mfma_f32_16x16x32_bf16 v[84:87], v[140:143], v[208:211], v[84:87]
	v_mfma_f32_16x16x32_bf16 v[76:79], v[132:135], v[216:219], v[76:79]
	v_mfma_f32_16x16x32_bf16 v[68:71], v[140:143], v[216:219], v[68:71]
	s_setprio 0
	s_setprio 1
	v_mfma_f32_16x16x32_bf16 v[120:123], v[154:157], v[188:191], v[120:123]
	v_mfma_f32_16x16x32_bf16 v[112:115], v[162:165], v[188:191], v[112:115]
	v_mfma_f32_16x16x32_bf16 v[104:107], v[154:157], v[196:199], v[104:107]
	v_mfma_f32_16x16x32_bf16 v[96:99], v[162:165], v[196:199], v[96:99]
	v_mfma_f32_16x16x32_bf16 v[88:91], v[154:157], v[204:207], v[88:91]
	v_mfma_f32_16x16x32_bf16 v[80:83], v[162:165], v[204:207], v[80:83]
	v_mfma_f32_16x16x32_bf16 v[72:75], v[154:157], v[212:215], v[72:75]
	v_mfma_f32_16x16x32_bf16 v[64:67], v[162:165], v[212:215], v[64:67]
	v_mfma_f32_16x16x32_bf16 v[120:123], v[158:161], v[192:195], v[120:123]
	v_mfma_f32_16x16x32_bf16 v[112:115], v[166:169], v[192:195], v[112:115]
	v_mfma_f32_16x16x32_bf16 v[104:107], v[158:161], v[200:203], v[104:107]
	v_mfma_f32_16x16x32_bf16 v[96:99], v[166:169], v[200:203], v[96:99]
	v_mfma_f32_16x16x32_bf16 v[88:91], v[158:161], v[208:211], v[88:91]
	v_mfma_f32_16x16x32_bf16 v[80:83], v[166:169], v[208:211], v[80:83]
	v_mfma_f32_16x16x32_bf16 v[72:75], v[158:161], v[216:219], v[72:75]
	v_mfma_f32_16x16x32_bf16 v[64:67], v[166:169], v[216:219], v[64:67]
	s_barrier
	s_setprio 0
	s_add_i32 s41, s41, s24
	v_lshl_add_u64 v[170:171], s[18:19], 0, v[146:147]
	s_mov_b32 m0, s41
	ds_read_b128 v[188:191], v186 offset:16384
	ds_read_b128 v[192:195], v186 offset:17408
	ds_read_b128 v[196:199], v186 offset:18432
	ds_read_b128 v[200:203], v186 offset:19456
	ds_read_b128 v[204:207], v186 offset:20480
	ds_read_b128 v[208:211], v186 offset:21504
	ds_read_b128 v[212:215], v186 offset:22528
	ds_read_b128 v[216:219], v186 offset:23552
	global_load_lds_dwordx4 v[170:171], off
	s_add_i32 m0, s41, 0x2000
	s_add_u32 s42, s18, 0x80000
	v_lshl_add_u64 v[228:229], s[18:19], 0, v[144:145]
	s_addc_u32 s43, s19, 0
	s_add_i32 s41, s44, s24
	global_load_lds_dwordx4 v[228:229], off
	v_lshl_add_u64 v[230:231], s[42:43], 0, v[146:147]
	s_mov_b32 m0, s41
	v_lshl_add_u64 v[236:237], s[20:21], 0, v[144:145]
	global_load_lds_dwordx4 v[230:231], off
	v_lshl_add_u64 v[230:231], s[42:43], 0, v[144:145]
	s_add_i32 m0, s41, 0x2000
	s_nop 0
	global_load_lds_dwordx4 v[230:231], off
	v_lshl_add_u64 v[230:231], s[20:21], 0, v[146:147]
	s_mov_b32 m0, s25
	s_nop 0
	global_load_lds_dwordx4 v[230:231], off
	s_mov_b32 m0, s26
	s_nop 0
	global_load_lds_dwordx4 v[236:237], off
	s_waitcnt vmcnt(8)
	s_waitcnt lgkmcnt(0)
	s_setprio 1
	s_barrier
	v_mfma_f32_16x16x32_bf16 v[60:63], v[128:131], v[188:191], v[60:63]
	v_mfma_f32_16x16x32_bf16 v[52:55], v[136:139], v[188:191], v[52:55]
	v_mfma_f32_16x16x32_bf16 v[44:47], v[128:131], v[196:199], v[44:47]
	v_mfma_f32_16x16x32_bf16 v[36:39], v[136:139], v[196:199], v[36:39]
	v_mfma_f32_16x16x32_bf16 v[28:31], v[128:131], v[204:207], v[28:31]
	v_mfma_f32_16x16x32_bf16 v[20:23], v[136:139], v[204:207], v[20:23]
	v_mfma_f32_16x16x32_bf16 v[12:15], v[128:131], v[212:215], v[12:15]
	v_mfma_f32_16x16x32_bf16 v[4:7], v[136:139], v[212:215], v[4:7]
	v_mfma_f32_16x16x32_bf16 v[60:63], v[132:135], v[192:195], v[60:63]
	v_mfma_f32_16x16x32_bf16 v[52:55], v[140:143], v[192:195], v[52:55]
	v_mfma_f32_16x16x32_bf16 v[44:47], v[132:135], v[200:203], v[44:47]
	v_mfma_f32_16x16x32_bf16 v[36:39], v[140:143], v[200:203], v[36:39]
	v_mfma_f32_16x16x32_bf16 v[28:31], v[132:135], v[208:211], v[28:31]
	v_mfma_f32_16x16x32_bf16 v[20:23], v[140:143], v[208:211], v[20:23]
	v_mfma_f32_16x16x32_bf16 v[12:15], v[132:135], v[216:219], v[12:15]
	v_mfma_f32_16x16x32_bf16 v[4:7], v[140:143], v[216:219], v[4:7]
	s_setprio 0
	s_setprio 1
	v_mfma_f32_16x16x32_bf16 v[56:59], v[154:157], v[188:191], v[56:59]
	v_mfma_f32_16x16x32_bf16 v[48:51], v[162:165], v[188:191], v[48:51]
	v_mfma_f32_16x16x32_bf16 v[40:43], v[154:157], v[196:199], v[40:43]
	v_mfma_f32_16x16x32_bf16 v[32:35], v[162:165], v[196:199], v[32:35]
	v_mfma_f32_16x16x32_bf16 v[24:27], v[154:157], v[204:207], v[24:27]
	v_mfma_f32_16x16x32_bf16 v[16:19], v[162:165], v[204:207], v[16:19]
	v_mfma_f32_16x16x32_bf16 v[8:11], v[154:157], v[212:215], v[8:11]
	v_mfma_f32_16x16x32_bf16 v[0:3], v[162:165], v[212:215], v[0:3]
	v_mfma_f32_16x16x32_bf16 v[56:59], v[158:161], v[192:195], v[56:59]
	v_mfma_f32_16x16x32_bf16 v[48:51], v[166:169], v[192:195], v[48:51]
	v_mfma_f32_16x16x32_bf16 v[40:43], v[158:161], v[200:203], v[40:43]
	v_mfma_f32_16x16x32_bf16 v[32:35], v[166:169], v[200:203], v[32:35]
	v_mfma_f32_16x16x32_bf16 v[24:27], v[158:161], v[208:211], v[24:27]
	v_mfma_f32_16x16x32_bf16 v[16:19], v[166:169], v[208:211], v[16:19]
	v_mfma_f32_16x16x32_bf16 v[8:11], v[158:161], v[216:219], v[8:11]
	v_mfma_f32_16x16x32_bf16 v[0:3], v[166:169], v[216:219], v[0:3]
	s_barrier
	s_setprio 0
	s_add_i32 s41, 0, 0x18000
	s_add_i32 s42, 0, 0x1c000
	v_add_u32_e32 v140, s41, v175
	v_add_u32_e32 v166, s42, v175
	ds_read_b128 v[128:131], v140
	ds_read_b128 v[132:135], v140 offset:1024
	ds_read_b128 v[136:139], v140 offset:2048
	ds_read_b128 v[140:143], v140 offset:3072
	ds_read_b128 v[154:157], v166
	ds_read_b128 v[158:161], v166 offset:1024
	ds_read_b128 v[162:165], v166 offset:2048
	ds_read_b128 v[166:169], v166 offset:3072
	s_add_u32 s20, s20, 0x80000
	s_addc_u32 s21, s21, 0
	s_mov_b32 m0, s27
	v_lshl_add_u64 v[238:239], s[20:21], 0, v[146:147]
	ds_read_b128 v[188:191], v186 offset:32768
	ds_read_b128 v[192:195], v186 offset:33792
	ds_read_b128 v[196:199], v186 offset:34816
	ds_read_b128 v[200:203], v186 offset:35840
	ds_read_b128 v[204:207], v186 offset:36864
	ds_read_b128 v[208:211], v186 offset:37888
	ds_read_b128 v[212:215], v186 offset:38912
	ds_read_b128 v[216:219], v186 offset:39936
	global_load_lds_dwordx4 v[238:239], off
	v_lshl_add_u64 v[238:239], s[20:21], 0, v[144:145]
	s_mov_b32 m0, s28
	s_nop 0
	global_load_lds_dwordx4 v[238:239], off
	s_waitcnt vmcnt(8)
	s_waitcnt lgkmcnt(0)
	s_setprio 1
	s_barrier
	v_mfma_f32_16x16x32_bf16 v[124:127], v[128:131], v[188:191], v[124:127]
	v_mfma_f32_16x16x32_bf16 v[116:119], v[136:139], v[188:191], v[116:119]
	v_mfma_f32_16x16x32_bf16 v[108:111], v[128:131], v[196:199], v[108:111]
	v_mfma_f32_16x16x32_bf16 v[100:103], v[136:139], v[196:199], v[100:103]
	v_mfma_f32_16x16x32_bf16 v[92:95], v[128:131], v[204:207], v[92:95]
	v_mfma_f32_16x16x32_bf16 v[84:87], v[136:139], v[204:207], v[84:87]
	v_mfma_f32_16x16x32_bf16 v[76:79], v[128:131], v[212:215], v[76:79]
	v_mfma_f32_16x16x32_bf16 v[68:71], v[136:139], v[212:215], v[68:71]
	v_mfma_f32_16x16x32_bf16 v[124:127], v[132:135], v[192:195], v[124:127]
	v_mfma_f32_16x16x32_bf16 v[116:119], v[140:143], v[192:195], v[116:119]
	v_mfma_f32_16x16x32_bf16 v[108:111], v[132:135], v[200:203], v[108:111]
	v_mfma_f32_16x16x32_bf16 v[100:103], v[140:143], v[200:203], v[100:103]
	v_mfma_f32_16x16x32_bf16 v[92:95], v[132:135], v[208:211], v[92:95]
	v_mfma_f32_16x16x32_bf16 v[84:87], v[140:143], v[208:211], v[84:87]
	v_mfma_f32_16x16x32_bf16 v[76:79], v[132:135], v[216:219], v[76:79]
	v_mfma_f32_16x16x32_bf16 v[68:71], v[140:143], v[216:219], v[68:71]
	s_setprio 0
	s_setprio 1
	v_mfma_f32_16x16x32_bf16 v[120:123], v[154:157], v[188:191], v[120:123]
	v_mfma_f32_16x16x32_bf16 v[112:115], v[162:165], v[188:191], v[112:115]
	v_mfma_f32_16x16x32_bf16 v[104:107], v[154:157], v[196:199], v[104:107]
	v_mfma_f32_16x16x32_bf16 v[96:99], v[162:165], v[196:199], v[96:99]
	v_mfma_f32_16x16x32_bf16 v[88:91], v[154:157], v[204:207], v[88:91]
	v_mfma_f32_16x16x32_bf16 v[80:83], v[162:165], v[204:207], v[80:83]
	v_mfma_f32_16x16x32_bf16 v[72:75], v[154:157], v[212:215], v[72:75]
	v_mfma_f32_16x16x32_bf16 v[64:67], v[162:165], v[212:215], v[64:67]
	v_mfma_f32_16x16x32_bf16 v[120:123], v[158:161], v[192:195], v[120:123]
	v_mfma_f32_16x16x32_bf16 v[112:115], v[166:169], v[192:195], v[112:115]
	v_mfma_f32_16x16x32_bf16 v[104:107], v[158:161], v[200:203], v[104:107]
	v_mfma_f32_16x16x32_bf16 v[96:99], v[166:169], v[200:203], v[96:99]
	v_mfma_f32_16x16x32_bf16 v[88:91], v[158:161], v[208:211], v[88:91]
	v_mfma_f32_16x16x32_bf16 v[80:83], v[166:169], v[208:211], v[80:83]
	v_mfma_f32_16x16x32_bf16 v[72:75], v[158:161], v[216:219], v[72:75]
	v_mfma_f32_16x16x32_bf16 v[64:67], v[166:169], v[216:219], v[64:67]
	s_barrier
	s_setprio 0
	s_add_i32 s20, s41, s24
	v_lshl_add_u64 v[170:171], v[170:171], 0, s[0:1]
	s_mov_b32 m0, s20
	ds_read_b128 v[188:191], v186 offset:49152
	ds_read_b128 v[192:195], v186 offset:50176
	ds_read_b128 v[196:199], v186 offset:51200
	ds_read_b128 v[200:203], v186 offset:52224
	ds_read_b128 v[204:207], v186 offset:53248
	ds_read_b128 v[208:211], v186 offset:54272
	ds_read_b128 v[212:215], v186 offset:55296
	ds_read_b128 v[216:219], v186 offset:56320
	global_load_lds_dwordx4 v[170:171], off
	s_add_i32 m0, s20, 0x2000
	s_add_u32 s18, s18, 0x80080
	v_lshl_add_u64 v[170:171], v[228:229], 0, s[0:1]
	s_addc_u32 s19, s19, 0
	s_add_i32 s20, s42, s24
	global_load_lds_dwordx4 v[170:171], off
	v_lshl_add_u64 v[170:171], s[18:19], 0, v[146:147]
	s_mov_b32 m0, s20
	s_nop 0
	global_load_lds_dwordx4 v[170:171], off
	v_lshl_add_u64 v[170:171], s[18:19], 0, v[144:145]
	s_add_i32 m0, s20, 0x2000
	s_nop 0
	global_load_lds_dwordx4 v[170:171], off
	v_lshl_add_u64 v[170:171], v[230:231], 0, s[0:1]
	s_mov_b32 m0, s29
	s_nop 0
	global_load_lds_dwordx4 v[170:171], off
	v_lshl_add_u64 v[170:171], v[236:237], 0, s[0:1]
	s_mov_b32 m0, s30
	s_nop 0
	global_load_lds_dwordx4 v[170:171], off
	s_waitcnt vmcnt(8)
	s_waitcnt lgkmcnt(0)
	s_setprio 1
	s_barrier
	v_mfma_f32_16x16x32_bf16 v[60:63], v[128:131], v[188:191], v[60:63]
	v_mfma_f32_16x16x32_bf16 v[52:55], v[136:139], v[188:191], v[52:55]
	v_mfma_f32_16x16x32_bf16 v[44:47], v[128:131], v[196:199], v[44:47]
	v_mfma_f32_16x16x32_bf16 v[36:39], v[136:139], v[196:199], v[36:39]
	v_mfma_f32_16x16x32_bf16 v[28:31], v[128:131], v[204:207], v[28:31]
	v_mfma_f32_16x16x32_bf16 v[20:23], v[136:139], v[204:207], v[20:23]
	v_mfma_f32_16x16x32_bf16 v[12:15], v[128:131], v[212:215], v[12:15]
	v_mfma_f32_16x16x32_bf16 v[4:7], v[136:139], v[212:215], v[4:7]
	v_mfma_f32_16x16x32_bf16 v[60:63], v[132:135], v[192:195], v[60:63]
	v_mfma_f32_16x16x32_bf16 v[52:55], v[140:143], v[192:195], v[52:55]
	v_mfma_f32_16x16x32_bf16 v[44:47], v[132:135], v[200:203], v[44:47]
	v_mfma_f32_16x16x32_bf16 v[36:39], v[140:143], v[200:203], v[36:39]
	v_mfma_f32_16x16x32_bf16 v[28:31], v[132:135], v[208:211], v[28:31]
	v_mfma_f32_16x16x32_bf16 v[20:23], v[140:143], v[208:211], v[20:23]
	v_mfma_f32_16x16x32_bf16 v[12:15], v[132:135], v[216:219], v[12:15]
	v_mfma_f32_16x16x32_bf16 v[4:7], v[140:143], v[216:219], v[4:7]
	s_setprio 0
	s_setprio 1
	v_mfma_f32_16x16x32_bf16 v[56:59], v[154:157], v[188:191], v[56:59]
	v_mfma_f32_16x16x32_bf16 v[48:51], v[162:165], v[188:191], v[48:51]
	v_mfma_f32_16x16x32_bf16 v[40:43], v[154:157], v[196:199], v[40:43]
	v_mfma_f32_16x16x32_bf16 v[32:35], v[162:165], v[196:199], v[32:35]
	v_mfma_f32_16x16x32_bf16 v[24:27], v[154:157], v[204:207], v[24:27]
	v_mfma_f32_16x16x32_bf16 v[16:19], v[162:165], v[204:207], v[16:19]
	v_mfma_f32_16x16x32_bf16 v[8:11], v[154:157], v[212:215], v[8:11]
	v_mfma_f32_16x16x32_bf16 v[0:3], v[162:165], v[212:215], v[0:3]
	v_mfma_f32_16x16x32_bf16 v[56:59], v[158:161], v[192:195], v[56:59]
	v_mfma_f32_16x16x32_bf16 v[48:51], v[166:169], v[192:195], v[48:51]
	v_mfma_f32_16x16x32_bf16 v[40:43], v[158:161], v[200:203], v[40:43]
	v_mfma_f32_16x16x32_bf16 v[32:35], v[166:169], v[200:203], v[32:35]
	v_mfma_f32_16x16x32_bf16 v[24:27], v[158:161], v[208:211], v[24:27]
	v_mfma_f32_16x16x32_bf16 v[16:19], v[166:169], v[208:211], v[16:19]
	v_mfma_f32_16x16x32_bf16 v[8:11], v[158:161], v[216:219], v[8:11]
	v_mfma_f32_16x16x32_bf16 v[0:3], v[166:169], v[216:219], v[0:3]
	s_barrier
	s_setprio 0
	s_add_i32 s40, s40, 2
	s_add_u32 s38, s38, 0x100
	s_addc_u32 s39, s39, 0
	s_add_u32 s6, s6, 0x100
	s_addc_u32 s7, s7, 0
	s_cmp_gt_u32 s40, 29
	s_cbranch_scc0 .LBB0_22
	s_and_b64 vcc, exec, s[8:9]
	s_cbranch_vccz .LBB0_25
	s_barrier

.LBB0_50:
	s_add_u32 s24, s2, 0x100
	s_addc_u32 s25, s3, 0
	s_add_i32 s52, 0, 0x10000
	s_cmp_eq_u32 s51, 28
	s_cselect_b32 s29, s19, s25
	s_cselect_b32 s28, s47, s24
	s_cselect_b32 s27, s17, s50
	s_cselect_b32 s26, s48, s49
	s_add_i32 s53, 0, 0x14000
	v_add_u32_e32 v140, s52, v236
	v_add_u32_e32 v156, s53, v236
	s_waitcnt lgkmcnt(0)
	ds_read_b128 v[128:131], v140
	ds_read_b128 v[132:135], v140 offset:1024
	ds_read_b128 v[136:139], v140 offset:2048
	ds_read_b128 v[140:143], v140 offset:3072
	ds_read_b128 v[144:147], v156
	ds_read_b128 v[148:151], v156 offset:1024
	ds_read_b128 v[152:155], v156 offset:2048
	ds_read_b128 v[156:159], v156 offset:3072
	v_lshl_add_u64 v[208:209], s[2:3], 0, v[190:191]
	s_add_i32 m0, s37, 0xc000
	ds_read_b128 v[160:163], v238
	ds_read_b128 v[164:167], v238 offset:1024
	ds_read_b128 v[168:171], v238 offset:2048
	ds_read_b128 v[172:175], v238 offset:3072
	ds_read_b128 v[192:195], v238 offset:4096
	ds_read_b128 v[196:199], v238 offset:5120
	ds_read_b128 v[200:203], v238 offset:6144
	ds_read_b128 v[204:207], v238 offset:7168
	global_load_lds_dwordx4 v[208:209], off
	v_lshl_add_u64 v[208:209], s[2:3], 0, v[188:189]
	s_add_i32 m0, s37, 0xe000
	s_nop 0
	global_load_lds_dwordx4 v[208:209], off
	s_waitcnt vmcnt(8)
	s_waitcnt lgkmcnt(0)
	s_setprio 1
	s_barrier
	v_mfma_f32_16x16x32_bf16 v[124:127], v[128:131], v[160:163], v[124:127]
	v_mfma_f32_16x16x32_bf16 v[120:123], v[136:139], v[160:163], v[120:123]
	v_mfma_f32_16x16x32_bf16 v[108:111], v[128:131], v[168:171], v[108:111]
	v_mfma_f32_16x16x32_bf16 v[104:107], v[136:139], v[168:171], v[104:107]
	v_mfma_f32_16x16x32_bf16 v[92:95], v[128:131], v[192:195], v[92:95]
	v_mfma_f32_16x16x32_bf16 v[88:91], v[136:139], v[192:195], v[88:91]
	v_mfma_f32_16x16x32_bf16 v[76:79], v[128:131], v[200:203], v[76:79]
	v_mfma_f32_16x16x32_bf16 v[72:75], v[136:139], v[200:203], v[72:75]
	v_mfma_f32_16x16x32_bf16 v[124:127], v[132:135], v[164:167], v[124:127]
	v_mfma_f32_16x16x32_bf16 v[120:123], v[140:143], v[164:167], v[120:123]
	v_mfma_f32_16x16x32_bf16 v[108:111], v[132:135], v[172:175], v[108:111]
	v_mfma_f32_16x16x32_bf16 v[104:107], v[140:143], v[172:175], v[104:107]
	v_mfma_f32_16x16x32_bf16 v[92:95], v[132:135], v[196:199], v[92:95]
	v_mfma_f32_16x16x32_bf16 v[88:91], v[140:143], v[196:199], v[88:91]
	v_mfma_f32_16x16x32_bf16 v[76:79], v[132:135], v[204:207], v[76:79]
	v_mfma_f32_16x16x32_bf16 v[72:75], v[140:143], v[204:207], v[72:75]
	s_setprio 0
	s_setprio 1
	v_mfma_f32_16x16x32_bf16 v[116:119], v[144:147], v[160:163], v[116:119]
	v_mfma_f32_16x16x32_bf16 v[112:115], v[152:155], v[160:163], v[112:115]
	v_mfma_f32_16x16x32_bf16 v[100:103], v[144:147], v[168:171], v[100:103]
	v_mfma_f32_16x16x32_bf16 v[96:99], v[152:155], v[168:171], v[96:99]
	v_mfma_f32_16x16x32_bf16 v[84:87], v[144:147], v[192:195], v[84:87]
	v_mfma_f32_16x16x32_bf16 v[80:83], v[152:155], v[192:195], v[80:83]
	v_mfma_f32_16x16x32_bf16 v[68:71], v[144:147], v[200:203], v[68:71]
	v_mfma_f32_16x16x32_bf16 v[64:67], v[152:155], v[200:203], v[64:67]
	v_mfma_f32_16x16x32_bf16 v[116:119], v[148:151], v[164:167], v[116:119]
	v_mfma_f32_16x16x32_bf16 v[112:115], v[156:159], v[164:167], v[112:115]
	v_mfma_f32_16x16x32_bf16 v[100:103], v[148:151], v[172:175], v[100:103]
	v_mfma_f32_16x16x32_bf16 v[96:99], v[156:159], v[172:175], v[96:99]
	v_mfma_f32_16x16x32_bf16 v[84:87], v[148:151], v[196:199], v[84:87]
	v_mfma_f32_16x16x32_bf16 v[80:83], v[156:159], v[196:199], v[80:83]
	v_mfma_f32_16x16x32_bf16 v[68:71], v[148:151], v[204:207], v[68:71]
	v_mfma_f32_16x16x32_bf16 v[64:67], v[156:159], v[204:207], v[64:67]
	s_barrier
	s_setprio 0
	s_add_i32 s2, s52, s34
	v_lshl_add_u64 v[208:209], s[26:27], 0, v[176:177]
	s_mov_b32 m0, s2
	ds_read_b128 v[160:163], v238 offset:16384
	ds_read_b128 v[164:167], v238 offset:17408
	ds_read_b128 v[168:171], v238 offset:18432
	ds_read_b128 v[172:175], v238 offset:19456
	ds_read_b128 v[192:195], v238 offset:20480
	ds_read_b128 v[196:199], v238 offset:21504
	ds_read_b128 v[200:203], v238 offset:22528
	ds_read_b128 v[204:207], v238 offset:23552
	global_load_lds_dwordx4 v[208:209], off
	s_add_i32 m0, s2, 0x2000
	s_add_u32 s2, s26, 0x80000
	v_lshl_add_u64 v[210:211], s[26:27], 0, v[186:187]
	s_addc_u32 s3, s27, 0
	s_add_i32 s52, s53, s34
	global_load_lds_dwordx4 v[210:211], off
	v_lshl_add_u64 v[212:213], s[2:3], 0, v[176:177]
	s_mov_b32 m0, s52
	v_lshl_add_u64 v[214:215], s[28:29], 0, v[186:187]
	global_load_lds_dwordx4 v[212:213], off
	v_lshl_add_u64 v[212:213], s[2:3], 0, v[186:187]
	s_add_i32 m0, s52, 0x2000
	s_nop 0
	global_load_lds_dwordx4 v[212:213], off
	v_lshl_add_u64 v[212:213], s[28:29], 0, v[176:177]
	s_mov_b32 m0, s37
	s_nop 0
	global_load_lds_dwordx4 v[212:213], off
	s_mov_b32 m0, s38
	s_nop 0
	global_load_lds_dwordx4 v[214:215], off
	s_waitcnt vmcnt(8)
	s_waitcnt lgkmcnt(0)
	s_setprio 1
	s_barrier
	v_mfma_f32_16x16x32_bf16 v[60:63], v[128:131], v[160:163], v[60:63]
	v_mfma_f32_16x16x32_bf16 v[56:59], v[136:139], v[160:163], v[56:59]
	v_mfma_f32_16x16x32_bf16 v[44:47], v[128:131], v[168:171], v[44:47]
	v_mfma_f32_16x16x32_bf16 v[40:43], v[136:139], v[168:171], v[40:43]
	v_mfma_f32_16x16x32_bf16 v[28:31], v[128:131], v[192:195], v[28:31]
	v_mfma_f32_16x16x32_bf16 v[24:27], v[136:139], v[192:195], v[24:27]
	v_mfma_f32_16x16x32_bf16 v[12:15], v[128:131], v[200:203], v[12:15]
	v_mfma_f32_16x16x32_bf16 v[8:11], v[136:139], v[200:203], v[8:11]
	v_mfma_f32_16x16x32_bf16 v[60:63], v[132:135], v[164:167], v[60:63]
	v_mfma_f32_16x16x32_bf16 v[56:59], v[140:143], v[164:167], v[56:59]
	v_mfma_f32_16x16x32_bf16 v[44:47], v[132:135], v[172:175], v[44:47]
	v_mfma_f32_16x16x32_bf16 v[40:43], v[140:143], v[172:175], v[40:43]
	v_mfma_f32_16x16x32_bf16 v[28:31], v[132:135], v[196:199], v[28:31]
	v_mfma_f32_16x16x32_bf16 v[24:27], v[140:143], v[196:199], v[24:27]
	v_mfma_f32_16x16x32_bf16 v[12:15], v[132:135], v[204:207], v[12:15]
	v_mfma_f32_16x16x32_bf16 v[8:11], v[140:143], v[204:207], v[8:11]
	s_setprio 0
	s_setprio 1
	v_mfma_f32_16x16x32_bf16 v[52:55], v[144:147], v[160:163], v[52:55]
	v_mfma_f32_16x16x32_bf16 v[48:51], v[152:155], v[160:163], v[48:51]
	v_mfma_f32_16x16x32_bf16 v[36:39], v[144:147], v[168:171], v[36:39]
	v_mfma_f32_16x16x32_bf16 v[32:35], v[152:155], v[168:171], v[32:35]
	v_mfma_f32_16x16x32_bf16 v[20:23], v[144:147], v[192:195], v[20:23]
	v_mfma_f32_16x16x32_bf16 v[16:19], v[152:155], v[192:195], v[16:19]
	v_mfma_f32_16x16x32_bf16 v[4:7], v[144:147], v[200:203], v[4:7]
	v_mfma_f32_16x16x32_bf16 v[0:3], v[152:155], v[200:203], v[0:3]
	v_mfma_f32_16x16x32_bf16 v[52:55], v[148:151], v[164:167], v[52:55]
	v_mfma_f32_16x16x32_bf16 v[48:51], v[156:159], v[164:167], v[48:51]
	v_mfma_f32_16x16x32_bf16 v[36:39], v[148:151], v[172:175], v[36:39]
	v_mfma_f32_16x16x32_bf16 v[32:35], v[156:159], v[172:175], v[32:35]
	v_mfma_f32_16x16x32_bf16 v[20:23], v[148:151], v[196:199], v[20:23]
	v_mfma_f32_16x16x32_bf16 v[16:19], v[156:159], v[196:199], v[16:19]
	v_mfma_f32_16x16x32_bf16 v[4:7], v[148:151], v[204:207], v[4:7]
	v_mfma_f32_16x16x32_bf16 v[0:3], v[156:159], v[204:207], v[0:3]
	s_barrier
	s_setprio 0
	s_add_i32 s52, 0, 0x18000
	s_add_i32 s53, 0, 0x1c000
	v_add_u32_e32 v140, s52, v236
	v_add_u32_e32 v156, s53, v236
	ds_read_b128 v[128:131], v140
	ds_read_b128 v[132:135], v140 offset:1024
	ds_read_b128 v[136:139], v140 offset:2048
	ds_read_b128 v[140:143], v140 offset:3072
	ds_read_b128 v[144:147], v156
	ds_read_b128 v[148:151], v156 offset:1024
	ds_read_b128 v[152:155], v156 offset:2048
	ds_read_b128 v[156:159], v156 offset:3072
	s_add_u32 s2, s28, 0x80000
	s_addc_u32 s3, s29, 0
	s_mov_b32 m0, s39
	v_lshl_add_u64 v[216:217], s[2:3], 0, v[176:177]
	ds_read_b128 v[160:163], v238 offset:32768
	ds_read_b128 v[164:167], v238 offset:33792
	ds_read_b128 v[168:171], v238 offset:34816
	ds_read_b128 v[172:175], v238 offset:35840
	ds_read_b128 v[192:195], v238 offset:36864
	ds_read_b128 v[196:199], v238 offset:37888
	ds_read_b128 v[200:203], v238 offset:38912
	ds_read_b128 v[204:207], v238 offset:39936
	global_load_lds_dwordx4 v[216:217], off
	v_lshl_add_u64 v[216:217], s[2:3], 0, v[186:187]
	s_mov_b32 m0, s40
	s_nop 0
	global_load_lds_dwordx4 v[216:217], off
	s_waitcnt vmcnt(8)
	s_waitcnt lgkmcnt(0)
	s_setprio 1
	s_barrier
	v_mfma_f32_16x16x32_bf16 v[124:127], v[128:131], v[160:163], v[124:127]
	v_mfma_f32_16x16x32_bf16 v[120:123], v[136:139], v[160:163], v[120:123]
	v_mfma_f32_16x16x32_bf16 v[108:111], v[128:131], v[168:171], v[108:111]
	v_mfma_f32_16x16x32_bf16 v[104:107], v[136:139], v[168:171], v[104:107]
	v_mfma_f32_16x16x32_bf16 v[92:95], v[128:131], v[192:195], v[92:95]
	v_mfma_f32_16x16x32_bf16 v[88:91], v[136:139], v[192:195], v[88:91]
	v_mfma_f32_16x16x32_bf16 v[76:79], v[128:131], v[200:203], v[76:79]
	v_mfma_f32_16x16x32_bf16 v[72:75], v[136:139], v[200:203], v[72:75]
	v_mfma_f32_16x16x32_bf16 v[124:127], v[132:135], v[164:167], v[124:127]
	v_mfma_f32_16x16x32_bf16 v[120:123], v[140:143], v[164:167], v[120:123]
	v_mfma_f32_16x16x32_bf16 v[108:111], v[132:135], v[172:175], v[108:111]
	v_mfma_f32_16x16x32_bf16 v[104:107], v[140:143], v[172:175], v[104:107]
	v_mfma_f32_16x16x32_bf16 v[92:95], v[132:135], v[196:199], v[92:95]
	v_mfma_f32_16x16x32_bf16 v[88:91], v[140:143], v[196:199], v[88:91]
	v_mfma_f32_16x16x32_bf16 v[76:79], v[132:135], v[204:207], v[76:79]
	v_mfma_f32_16x16x32_bf16 v[72:75], v[140:143], v[204:207], v[72:75]
	s_setprio 0
	s_setprio 1
	v_mfma_f32_16x16x32_bf16 v[116:119], v[144:147], v[160:163], v[116:119]
	v_mfma_f32_16x16x32_bf16 v[112:115], v[152:155], v[160:163], v[112:115]
	v_mfma_f32_16x16x32_bf16 v[100:103], v[144:147], v[168:171], v[100:103]
	v_mfma_f32_16x16x32_bf16 v[96:99], v[152:155], v[168:171], v[96:99]
	v_mfma_f32_16x16x32_bf16 v[84:87], v[144:147], v[192:195], v[84:87]
	v_mfma_f32_16x16x32_bf16 v[80:83], v[152:155], v[192:195], v[80:83]
	v_mfma_f32_16x16x32_bf16 v[68:71], v[144:147], v[200:203], v[68:71]
	v_mfma_f32_16x16x32_bf16 v[64:67], v[152:155], v[200:203], v[64:67]
	v_mfma_f32_16x16x32_bf16 v[116:119], v[148:151], v[164:167], v[116:119]
	v_mfma_f32_16x16x32_bf16 v[112:115], v[156:159], v[164:167], v[112:115]
	v_mfma_f32_16x16x32_bf16 v[100:103], v[148:151], v[172:175], v[100:103]
	v_mfma_f32_16x16x32_bf16 v[96:99], v[156:159], v[172:175], v[96:99]
	v_mfma_f32_16x16x32_bf16 v[84:87], v[148:151], v[196:199], v[84:87]
	v_mfma_f32_16x16x32_bf16 v[80:83], v[156:159], v[196:199], v[80:83]
	v_mfma_f32_16x16x32_bf16 v[68:71], v[148:151], v[204:207], v[68:71]
	v_mfma_f32_16x16x32_bf16 v[64:67], v[156:159], v[204:207], v[64:67]
	s_barrier
	s_setprio 0
	s_add_i32 s2, s52, s34
	v_lshl_add_u64 v[208:209], v[208:209], 0, s[0:1]
	s_mov_b32 m0, s2
	ds_read_b128 v[160:163], v238 offset:49152
	ds_read_b128 v[164:167], v238 offset:50176
	ds_read_b128 v[168:171], v238 offset:51200
	ds_read_b128 v[172:175], v238 offset:52224
	ds_read_b128 v[192:195], v238 offset:53248
	ds_read_b128 v[196:199], v238 offset:54272
	ds_read_b128 v[200:203], v238 offset:55296
	ds_read_b128 v[204:207], v238 offset:56320
	global_load_lds_dwordx4 v[208:209], off
	s_add_i32 m0, s2, 0x2000
	s_add_u32 s2, s26, 0x80080
	v_lshl_add_u64 v[208:209], v[210:211], 0, s[0:1]
	s_addc_u32 s3, s27, 0
	s_add_i32 s26, s53, s34
	global_load_lds_dwordx4 v[208:209], off
	v_lshl_add_u64 v[208:209], s[2:3], 0, v[176:177]
	s_mov_b32 m0, s26
	s_nop 0
	global_load_lds_dwordx4 v[208:209], off
	v_lshl_add_u64 v[208:209], s[2:3], 0, v[186:187]
	s_add_i32 m0, s26, 0x2000
	s_nop 0
	global_load_lds_dwordx4 v[208:209], off
	v_lshl_add_u64 v[208:209], v[212:213], 0, s[0:1]
	s_mov_b32 m0, s42
	s_nop 0
	global_load_lds_dwordx4 v[208:209], off
	v_lshl_add_u64 v[208:209], v[214:215], 0, s[0:1]
	s_mov_b32 m0, s43
	s_nop 0
	global_load_lds_dwordx4 v[208:209], off
	s_waitcnt vmcnt(8)
	s_waitcnt lgkmcnt(0)
	s_setprio 1
	s_barrier
	v_mfma_f32_16x16x32_bf16 v[60:63], v[128:131], v[160:163], v[60:63]
	v_mfma_f32_16x16x32_bf16 v[56:59], v[136:139], v[160:163], v[56:59]
	v_mfma_f32_16x16x32_bf16 v[44:47], v[128:131], v[168:171], v[44:47]
	v_mfma_f32_16x16x32_bf16 v[40:43], v[136:139], v[168:171], v[40:43]
	v_mfma_f32_16x16x32_bf16 v[28:31], v[128:131], v[192:195], v[28:31]
	v_mfma_f32_16x16x32_bf16 v[24:27], v[136:139], v[192:195], v[24:27]
	v_mfma_f32_16x16x32_bf16 v[12:15], v[128:131], v[200:203], v[12:15]
	v_mfma_f32_16x16x32_bf16 v[8:11], v[136:139], v[200:203], v[8:11]
	v_mfma_f32_16x16x32_bf16 v[60:63], v[132:135], v[164:167], v[60:63]
	v_mfma_f32_16x16x32_bf16 v[56:59], v[140:143], v[164:167], v[56:59]
	v_mfma_f32_16x16x32_bf16 v[44:47], v[132:135], v[172:175], v[44:47]
	v_mfma_f32_16x16x32_bf16 v[40:43], v[140:143], v[172:175], v[40:43]
	v_mfma_f32_16x16x32_bf16 v[28:31], v[132:135], v[196:199], v[28:31]
	v_mfma_f32_16x16x32_bf16 v[24:27], v[140:143], v[196:199], v[24:27]
	v_mfma_f32_16x16x32_bf16 v[12:15], v[132:135], v[204:207], v[12:15]
	v_mfma_f32_16x16x32_bf16 v[8:11], v[140:143], v[204:207], v[8:11]
	s_setprio 0
	s_setprio 1
	v_mfma_f32_16x16x32_bf16 v[52:55], v[144:147], v[160:163], v[52:55]
	v_mfma_f32_16x16x32_bf16 v[48:51], v[152:155], v[160:163], v[48:51]
	v_mfma_f32_16x16x32_bf16 v[36:39], v[144:147], v[168:171], v[36:39]
	v_mfma_f32_16x16x32_bf16 v[32:35], v[152:155], v[168:171], v[32:35]
	v_mfma_f32_16x16x32_bf16 v[20:23], v[144:147], v[192:195], v[20:23]
	v_mfma_f32_16x16x32_bf16 v[16:19], v[152:155], v[192:195], v[16:19]
	v_mfma_f32_16x16x32_bf16 v[4:7], v[144:147], v[200:203], v[4:7]
	v_mfma_f32_16x16x32_bf16 v[0:3], v[152:155], v[200:203], v[0:3]
	v_mfma_f32_16x16x32_bf16 v[52:55], v[148:151], v[164:167], v[52:55]
	v_mfma_f32_16x16x32_bf16 v[48:51], v[156:159], v[164:167], v[48:51]
	v_mfma_f32_16x16x32_bf16 v[36:39], v[148:151], v[172:175], v[36:39]
	v_mfma_f32_16x16x32_bf16 v[32:35], v[156:159], v[172:175], v[32:35]
	v_mfma_f32_16x16x32_bf16 v[20:23], v[148:151], v[196:199], v[20:23]
	v_mfma_f32_16x16x32_bf16 v[16:19], v[156:159], v[196:199], v[16:19]
	v_mfma_f32_16x16x32_bf16 v[4:7], v[148:151], v[204:207], v[4:7]
	v_mfma_f32_16x16x32_bf16 v[0:3], v[156:159], v[204:207], v[0:3]
	s_barrier
	s_setprio 0
	s_add_i32 s51, s51, 2
	s_add_u32 s49, s49, 0x100
	s_addc_u32 s50, s50, 0
	s_cmp_gt_u32 s51, 29
	s_mov_b64 s[2:3], s[24:25]
	s_cbranch_scc0 .LBB0_50
	s_and_b64 vcc, exec, s[12:13]
	s_cbranch_vccz .LBB0_53
	s_barrier

.LBB0_291:
	s_add_u32 s8, s20, 0x100
	s_addc_u32 s9, s21, 0
	s_add_i32 s46, 0, 0x10000
	s_cmpk_eq_i32 s45, 0x54
	s_cselect_b32 s25, s17, s9
	s_cselect_b32 s24, s16, s8
	s_cselect_b32 s23, s19, s44
	s_cselect_b32 s22, s18, s43
	s_add_i32 s47, 0, 0x14000
	v_add_u32_e32 v146, s46, v215
	v_add_u32_e32 v162, s47, v215
	ds_read_b128 v[134:137], v146
	ds_read_b128 v[138:141], v146 offset:1024
	ds_read_b128 v[142:145], v146 offset:2048
	ds_read_b128 v[146:149], v146 offset:3072
	ds_read_b128 v[150:153], v162
	ds_read_b128 v[154:157], v162 offset:1024
	ds_read_b128 v[158:161], v162 offset:2048
	ds_read_b128 v[162:165], v162 offset:3072
	v_lshl_add_u64 v[174:175], s[20:21], 0, v[132:133]
	s_add_i32 m0, s29, 0xc000
	ds_read_b128 v[166:169], v217
	ds_read_b128 v[170:173], v217 offset:1024
	ds_read_b128 v[186:189], v217 offset:2048
	ds_read_b128 v[190:193], v217 offset:3072
	ds_read_b128 v[194:197], v217 offset:4096
	ds_read_b128 v[198:201], v217 offset:5120
	ds_read_b128 v[202:205], v217 offset:6144
	ds_read_b128 v[206:209], v217 offset:7168
	global_load_lds_dwordx4 v[174:175], off
	v_lshl_add_u64 v[174:175], s[20:21], 0, v[130:131]
	s_add_i32 m0, s29, 0xe000
	s_nop 0
	global_load_lds_dwordx4 v[174:175], off
	s_waitcnt vmcnt(8)
	s_waitcnt lgkmcnt(0)
	s_setprio 1
	s_barrier
	v_mfma_f32_16x16x32_bf16 v[124:127], v[134:137], v[166:169], v[124:127]
	v_mfma_f32_16x16x32_bf16 v[120:123], v[142:145], v[166:169], v[120:123]
	v_mfma_f32_16x16x32_bf16 v[108:111], v[134:137], v[186:189], v[108:111]
	v_mfma_f32_16x16x32_bf16 v[104:107], v[142:145], v[186:189], v[104:107]
	v_mfma_f32_16x16x32_bf16 v[92:95], v[134:137], v[194:197], v[92:95]
	v_mfma_f32_16x16x32_bf16 v[88:91], v[142:145], v[194:197], v[88:91]
	v_mfma_f32_16x16x32_bf16 v[76:79], v[134:137], v[202:205], v[76:79]
	v_mfma_f32_16x16x32_bf16 v[72:75], v[142:145], v[202:205], v[72:75]
	v_mfma_f32_16x16x32_bf16 v[124:127], v[138:141], v[170:173], v[124:127]
	v_mfma_f32_16x16x32_bf16 v[120:123], v[146:149], v[170:173], v[120:123]
	v_mfma_f32_16x16x32_bf16 v[108:111], v[138:141], v[190:193], v[108:111]
	v_mfma_f32_16x16x32_bf16 v[104:107], v[146:149], v[190:193], v[104:107]
	v_mfma_f32_16x16x32_bf16 v[92:95], v[138:141], v[198:201], v[92:95]
	v_mfma_f32_16x16x32_bf16 v[88:91], v[146:149], v[198:201], v[88:91]
	v_mfma_f32_16x16x32_bf16 v[76:79], v[138:141], v[206:209], v[76:79]
	v_mfma_f32_16x16x32_bf16 v[72:75], v[146:149], v[206:209], v[72:75]
	s_setprio 0
	s_setprio 1
	v_mfma_f32_16x16x32_bf16 v[116:119], v[150:153], v[166:169], v[116:119]
	v_mfma_f32_16x16x32_bf16 v[112:115], v[158:161], v[166:169], v[112:115]
	v_mfma_f32_16x16x32_bf16 v[100:103], v[150:153], v[186:189], v[100:103]
	v_mfma_f32_16x16x32_bf16 v[96:99], v[158:161], v[186:189], v[96:99]
	v_mfma_f32_16x16x32_bf16 v[84:87], v[150:153], v[194:197], v[84:87]
	v_mfma_f32_16x16x32_bf16 v[80:83], v[158:161], v[194:197], v[80:83]
	v_mfma_f32_16x16x32_bf16 v[68:71], v[150:153], v[202:205], v[68:71]
	v_mfma_f32_16x16x32_bf16 v[64:67], v[158:161], v[202:205], v[64:67]
	v_mfma_f32_16x16x32_bf16 v[116:119], v[154:157], v[170:173], v[116:119]
	v_mfma_f32_16x16x32_bf16 v[112:115], v[162:165], v[170:173], v[112:115]
	v_mfma_f32_16x16x32_bf16 v[100:103], v[154:157], v[190:193], v[100:103]
	v_mfma_f32_16x16x32_bf16 v[96:99], v[162:165], v[190:193], v[96:99]
	v_mfma_f32_16x16x32_bf16 v[84:87], v[154:157], v[198:201], v[84:87]
	v_mfma_f32_16x16x32_bf16 v[80:83], v[162:165], v[198:201], v[80:83]
	v_mfma_f32_16x16x32_bf16 v[68:71], v[154:157], v[206:209], v[68:71]
	v_mfma_f32_16x16x32_bf16 v[64:67], v[162:165], v[206:209], v[64:67]
	s_barrier
	s_setprio 0
	s_add_i32 s20, s46, s28
	v_lshl_add_u64 v[174:175], s[22:23], 0, v[176:177]
	s_mov_b32 m0, s20
	ds_read_b128 v[166:169], v217 offset:16384
	ds_read_b128 v[170:173], v217 offset:17408
	ds_read_b128 v[186:189], v217 offset:18432
	ds_read_b128 v[190:193], v217 offset:19456
	ds_read_b128 v[194:197], v217 offset:20480
	ds_read_b128 v[198:201], v217 offset:21504
	ds_read_b128 v[202:205], v217 offset:22528
	ds_read_b128 v[206:209], v217 offset:23552
	global_load_lds_dwordx4 v[174:175], off
	s_add_i32 m0, s20, 0x2000
	s_add_u32 s20, s22, 0x160000
	v_lshl_add_u64 v[210:211], s[22:23], 0, v[128:129]
	s_addc_u32 s21, s23, 0
	s_add_i32 s46, s47, s28
	global_load_lds_dwordx4 v[210:211], off
	v_lshl_add_u64 v[212:213], s[20:21], 0, v[176:177]
	s_mov_b32 m0, s46
	v_lshl_add_u64 v[218:219], s[24:25], 0, v[128:129]
	global_load_lds_dwordx4 v[212:213], off
	v_lshl_add_u64 v[212:213], s[20:21], 0, v[128:129]
	s_add_i32 m0, s46, 0x2000
	s_nop 0
	global_load_lds_dwordx4 v[212:213], off
	v_lshl_add_u64 v[212:213], s[24:25], 0, v[176:177]
	s_mov_b32 m0, s29
	s_nop 0
	global_load_lds_dwordx4 v[212:213], off
	s_mov_b32 m0, s30
	s_nop 0
	global_load_lds_dwordx4 v[218:219], off
	s_waitcnt vmcnt(8)
	s_waitcnt lgkmcnt(0)
	s_setprio 1
	s_barrier
	v_mfma_f32_16x16x32_bf16 v[60:63], v[134:137], v[166:169], v[60:63]
	v_mfma_f32_16x16x32_bf16 v[56:59], v[142:145], v[166:169], v[56:59]
	v_mfma_f32_16x16x32_bf16 v[44:47], v[134:137], v[186:189], v[44:47]
	v_mfma_f32_16x16x32_bf16 v[40:43], v[142:145], v[186:189], v[40:43]
	v_mfma_f32_16x16x32_bf16 v[28:31], v[134:137], v[194:197], v[28:31]
	v_mfma_f32_16x16x32_bf16 v[24:27], v[142:145], v[194:197], v[24:27]
	v_mfma_f32_16x16x32_bf16 v[12:15], v[134:137], v[202:205], v[12:15]
	v_mfma_f32_16x16x32_bf16 v[8:11], v[142:145], v[202:205], v[8:11]
	v_mfma_f32_16x16x32_bf16 v[60:63], v[138:141], v[170:173], v[60:63]
	v_mfma_f32_16x16x32_bf16 v[56:59], v[146:149], v[170:173], v[56:59]
	v_mfma_f32_16x16x32_bf16 v[44:47], v[138:141], v[190:193], v[44:47]
	v_mfma_f32_16x16x32_bf16 v[40:43], v[146:149], v[190:193], v[40:43]
	v_mfma_f32_16x16x32_bf16 v[28:31], v[138:141], v[198:201], v[28:31]
	v_mfma_f32_16x16x32_bf16 v[24:27], v[146:149], v[198:201], v[24:27]
	v_mfma_f32_16x16x32_bf16 v[12:15], v[138:141], v[206:209], v[12:15]
	v_mfma_f32_16x16x32_bf16 v[8:11], v[146:149], v[206:209], v[8:11]
	s_setprio 0
	s_setprio 1
	v_mfma_f32_16x16x32_bf16 v[52:55], v[150:153], v[166:169], v[52:55]
	v_mfma_f32_16x16x32_bf16 v[48:51], v[158:161], v[166:169], v[48:51]
	v_mfma_f32_16x16x32_bf16 v[36:39], v[150:153], v[186:189], v[36:39]
	v_mfma_f32_16x16x32_bf16 v[32:35], v[158:161], v[186:189], v[32:35]
	v_mfma_f32_16x16x32_bf16 v[20:23], v[150:153], v[194:197], v[20:23]
	v_mfma_f32_16x16x32_bf16 v[16:19], v[158:161], v[194:197], v[16:19]
	v_mfma_f32_16x16x32_bf16 v[4:7], v[150:153], v[202:205], v[4:7]
	v_mfma_f32_16x16x32_bf16 v[0:3], v[158:161], v[202:205], v[0:3]
	v_mfma_f32_16x16x32_bf16 v[52:55], v[154:157], v[170:173], v[52:55]
	v_mfma_f32_16x16x32_bf16 v[48:51], v[162:165], v[170:173], v[48:51]
	v_mfma_f32_16x16x32_bf16 v[36:39], v[154:157], v[190:193], v[36:39]
	v_mfma_f32_16x16x32_bf16 v[32:35], v[162:165], v[190:193], v[32:35]
	v_mfma_f32_16x16x32_bf16 v[20:23], v[154:157], v[198:201], v[20:23]
	v_mfma_f32_16x16x32_bf16 v[16:19], v[162:165], v[198:201], v[16:19]
	v_mfma_f32_16x16x32_bf16 v[4:7], v[154:157], v[206:209], v[4:7]
	v_mfma_f32_16x16x32_bf16 v[0:3], v[162:165], v[206:209], v[0:3]
	s_barrier
	s_setprio 0
	s_add_i32 s46, 0, 0x18000
	s_add_i32 s47, 0, 0x1c000
	v_add_u32_e32 v146, s46, v215
	v_add_u32_e32 v162, s47, v215
	ds_read_b128 v[134:137], v146
	ds_read_b128 v[138:141], v146 offset:1024
	ds_read_b128 v[142:145], v146 offset:2048
	ds_read_b128 v[146:149], v146 offset:3072
	ds_read_b128 v[150:153], v162
	ds_read_b128 v[154:157], v162 offset:1024
	ds_read_b128 v[158:161], v162 offset:2048
	ds_read_b128 v[162:165], v162 offset:3072
	s_add_u32 s20, s24, 0x160000
	s_addc_u32 s21, s25, 0
	s_mov_b32 m0, s31
	v_lshl_add_u64 v[228:229], s[20:21], 0, v[176:177]
	ds_read_b128 v[166:169], v217 offset:32768
	ds_read_b128 v[170:173], v217 offset:33792
	ds_read_b128 v[186:189], v217 offset:34816
	ds_read_b128 v[190:193], v217 offset:35840
	ds_read_b128 v[194:197], v217 offset:36864
	ds_read_b128 v[198:201], v217 offset:37888
	ds_read_b128 v[202:205], v217 offset:38912
	ds_read_b128 v[206:209], v217 offset:39936
	global_load_lds_dwordx4 v[228:229], off
	v_lshl_add_u64 v[228:229], s[20:21], 0, v[128:129]
	s_mov_b32 m0, s34
	s_nop 0
	global_load_lds_dwordx4 v[228:229], off
	s_waitcnt vmcnt(8)
	s_waitcnt lgkmcnt(0)
	s_setprio 1
	s_barrier
	v_mfma_f32_16x16x32_bf16 v[124:127], v[134:137], v[166:169], v[124:127]
	v_mfma_f32_16x16x32_bf16 v[120:123], v[142:145], v[166:169], v[120:123]
	v_mfma_f32_16x16x32_bf16 v[108:111], v[134:137], v[186:189], v[108:111]
	v_mfma_f32_16x16x32_bf16 v[104:107], v[142:145], v[186:189], v[104:107]
	v_mfma_f32_16x16x32_bf16 v[92:95], v[134:137], v[194:197], v[92:95]
	v_mfma_f32_16x16x32_bf16 v[88:91], v[142:145], v[194:197], v[88:91]
	v_mfma_f32_16x16x32_bf16 v[76:79], v[134:137], v[202:205], v[76:79]
	v_mfma_f32_16x16x32_bf16 v[72:75], v[142:145], v[202:205], v[72:75]
	v_mfma_f32_16x16x32_bf16 v[124:127], v[138:141], v[170:173], v[124:127]
	v_mfma_f32_16x16x32_bf16 v[120:123], v[146:149], v[170:173], v[120:123]
	v_mfma_f32_16x16x32_bf16 v[108:111], v[138:141], v[190:193], v[108:111]
	v_mfma_f32_16x16x32_bf16 v[104:107], v[146:149], v[190:193], v[104:107]
	v_mfma_f32_16x16x32_bf16 v[92:95], v[138:141], v[198:201], v[92:95]
	v_mfma_f32_16x16x32_bf16 v[88:91], v[146:149], v[198:201], v[88:91]
	v_mfma_f32_16x16x32_bf16 v[76:79], v[138:141], v[206:209], v[76:79]
	v_mfma_f32_16x16x32_bf16 v[72:75], v[146:149], v[206:209], v[72:75]
	s_setprio 0
	s_setprio 1
	v_mfma_f32_16x16x32_bf16 v[116:119], v[150:153], v[166:169], v[116:119]
	v_mfma_f32_16x16x32_bf16 v[112:115], v[158:161], v[166:169], v[112:115]
	v_mfma_f32_16x16x32_bf16 v[100:103], v[150:153], v[186:189], v[100:103]
	v_mfma_f32_16x16x32_bf16 v[96:99], v[158:161], v[186:189], v[96:99]
	v_mfma_f32_16x16x32_bf16 v[84:87], v[150:153], v[194:197], v[84:87]
	v_mfma_f32_16x16x32_bf16 v[80:83], v[158:161], v[194:197], v[80:83]
	v_mfma_f32_16x16x32_bf16 v[68:71], v[150:153], v[202:205], v[68:71]
	v_mfma_f32_16x16x32_bf16 v[64:67], v[158:161], v[202:205], v[64:67]
	v_mfma_f32_16x16x32_bf16 v[116:119], v[154:157], v[170:173], v[116:119]
	v_mfma_f32_16x16x32_bf16 v[112:115], v[162:165], v[170:173], v[112:115]
	v_mfma_f32_16x16x32_bf16 v[100:103], v[154:157], v[190:193], v[100:103]
	v_mfma_f32_16x16x32_bf16 v[96:99], v[162:165], v[190:193], v[96:99]
	v_mfma_f32_16x16x32_bf16 v[84:87], v[154:157], v[198:201], v[84:87]
	v_mfma_f32_16x16x32_bf16 v[80:83], v[162:165], v[198:201], v[80:83]
	v_mfma_f32_16x16x32_bf16 v[68:71], v[154:157], v[206:209], v[68:71]
	v_mfma_f32_16x16x32_bf16 v[64:67], v[162:165], v[206:209], v[64:67]
	s_barrier
	s_setprio 0
	s_add_i32 s20, s46, s28
	v_lshl_add_u64 v[174:175], v[174:175], 0, s[0:1]
	s_mov_b32 m0, s20
	ds_read_b128 v[166:169], v217 offset:49152
	ds_read_b128 v[170:173], v217 offset:50176
	ds_read_b128 v[186:189], v217 offset:51200
	ds_read_b128 v[190:193], v217 offset:52224
	ds_read_b128 v[194:197], v217 offset:53248
	ds_read_b128 v[198:201], v217 offset:54272
	ds_read_b128 v[202:205], v217 offset:55296
	ds_read_b128 v[206:209], v217 offset:56320
	global_load_lds_dwordx4 v[174:175], off
	s_add_i32 m0, s20, 0x2000
	s_add_u32 s20, s22, 0x160080
	v_lshl_add_u64 v[174:175], v[210:211], 0, s[0:1]
	s_addc_u32 s21, s23, 0
	s_add_i32 s22, s47, s28
	global_load_lds_dwordx4 v[174:175], off
	v_lshl_add_u64 v[174:175], s[20:21], 0, v[176:177]
	s_mov_b32 m0, s22
	s_nop 0
	global_load_lds_dwordx4 v[174:175], off
	v_lshl_add_u64 v[174:175], s[20:21], 0, v[128:129]
	s_add_i32 m0, s22, 0x2000
	s_nop 0
	global_load_lds_dwordx4 v[174:175], off
	v_lshl_add_u64 v[174:175], v[212:213], 0, s[0:1]
	s_mov_b32 m0, s36
	s_nop 0
	global_load_lds_dwordx4 v[174:175], off
	v_lshl_add_u64 v[174:175], v[218:219], 0, s[0:1]
	s_mov_b32 m0, s37
	s_nop 0
	global_load_lds_dwordx4 v[174:175], off
	s_waitcnt vmcnt(8)
	s_waitcnt lgkmcnt(0)
	s_setprio 1
	s_barrier
	v_mfma_f32_16x16x32_bf16 v[60:63], v[134:137], v[166:169], v[60:63]
	v_mfma_f32_16x16x32_bf16 v[56:59], v[142:145], v[166:169], v[56:59]
	v_mfma_f32_16x16x32_bf16 v[44:47], v[134:137], v[186:189], v[44:47]
	v_mfma_f32_16x16x32_bf16 v[40:43], v[142:145], v[186:189], v[40:43]
	v_mfma_f32_16x16x32_bf16 v[28:31], v[134:137], v[194:197], v[28:31]
	v_mfma_f32_16x16x32_bf16 v[24:27], v[142:145], v[194:197], v[24:27]
	v_mfma_f32_16x16x32_bf16 v[12:15], v[134:137], v[202:205], v[12:15]
	v_mfma_f32_16x16x32_bf16 v[8:11], v[142:145], v[202:205], v[8:11]
	v_mfma_f32_16x16x32_bf16 v[60:63], v[138:141], v[170:173], v[60:63]
	v_mfma_f32_16x16x32_bf16 v[56:59], v[146:149], v[170:173], v[56:59]
	v_mfma_f32_16x16x32_bf16 v[44:47], v[138:141], v[190:193], v[44:47]
	v_mfma_f32_16x16x32_bf16 v[40:43], v[146:149], v[190:193], v[40:43]
	v_mfma_f32_16x16x32_bf16 v[28:31], v[138:141], v[198:201], v[28:31]
	v_mfma_f32_16x16x32_bf16 v[24:27], v[146:149], v[198:201], v[24:27]
	v_mfma_f32_16x16x32_bf16 v[12:15], v[138:141], v[206:209], v[12:15]
	v_mfma_f32_16x16x32_bf16 v[8:11], v[146:149], v[206:209], v[8:11]
	s_setprio 0
	s_setprio 1
	v_mfma_f32_16x16x32_bf16 v[52:55], v[150:153], v[166:169], v[52:55]
	v_mfma_f32_16x16x32_bf16 v[48:51], v[158:161], v[166:169], v[48:51]
	v_mfma_f32_16x16x32_bf16 v[36:39], v[150:153], v[186:189], v[36:39]
	v_mfma_f32_16x16x32_bf16 v[32:35], v[158:161], v[186:189], v[32:35]
	v_mfma_f32_16x16x32_bf16 v[20:23], v[150:153], v[194:197], v[20:23]
	v_mfma_f32_16x16x32_bf16 v[16:19], v[158:161], v[194:197], v[16:19]
	v_mfma_f32_16x16x32_bf16 v[4:7], v[150:153], v[202:205], v[4:7]
	v_mfma_f32_16x16x32_bf16 v[0:3], v[158:161], v[202:205], v[0:3]
	v_mfma_f32_16x16x32_bf16 v[52:55], v[154:157], v[170:173], v[52:55]
	v_mfma_f32_16x16x32_bf16 v[48:51], v[162:165], v[170:173], v[48:51]
	v_mfma_f32_16x16x32_bf16 v[36:39], v[154:157], v[190:193], v[36:39]
	v_mfma_f32_16x16x32_bf16 v[32:35], v[162:165], v[190:193], v[32:35]
	v_mfma_f32_16x16x32_bf16 v[20:23], v[154:157], v[198:201], v[20:23]
	v_mfma_f32_16x16x32_bf16 v[16:19], v[162:165], v[198:201], v[16:19]
	v_mfma_f32_16x16x32_bf16 v[4:7], v[154:157], v[206:209], v[4:7]
	v_mfma_f32_16x16x32_bf16 v[0:3], v[162:165], v[206:209], v[0:3]
	s_barrier
	s_setprio 0
	s_add_i32 s45, s45, 2
	s_add_u32 s43, s43, 0x100
	s_addc_u32 s44, s44, 0
	s_cmpk_gt_u32 s45, 0x55
	s_mov_b64 s[20:21], s[8:9]
	s_cbranch_scc0 .LBB0_291
	s_and_b64 vcc, exec, s[14:15]
	s_cbranch_vccz .LBB0_294
	s_barrier

.LBB0_474:
	s_add_u32 s20, s18, 0xfff80080
	s_addc_u32 s21, s19, -1
	s_add_i32 s45, 0, 0x10000
	s_cmp_eq_u32 s44, 28
	s_cselect_b32 s23, s13, s21
	s_cselect_b32 s22, s40, s20
	v_add_u32_e32 v139, s45, v137
	s_cselect_b32 s21, s11, s43
	s_cselect_b32 s20, s41, s42
	s_add_i32 s48, 0, 0x14000
	ds_read_b128 v[140:143], v139
	ds_read_b128 v[144:147], v139 offset:1024
	ds_read_b128 v[148:151], v139 offset:2048
	ds_read_b128 v[152:155], v139 offset:3072
	v_add_u32_e32 v139, s48, v137
	ds_read_b128 v[156:159], v139
	ds_read_b128 v[160:163], v139 offset:1024
	ds_read_b128 v[164:167], v139 offset:2048
	ds_read_b128 v[168:171], v139 offset:3072
	v_lshl_add_u64 v[214:215], s[18:19], 0, v[134:135]
	s_add_i32 m0, s29, 0xc000
	ds_read_b128 v[172:175], v138
	ds_read_b128 v[186:189], v138 offset:1024
	ds_read_b128 v[190:193], v138 offset:2048
	ds_read_b128 v[194:197], v138 offset:3072
	ds_read_b128 v[198:201], v138 offset:4096
	ds_read_b128 v[202:205], v138 offset:5120
	ds_read_b128 v[206:209], v138 offset:6144
	ds_read_b128 v[210:213], v138 offset:7168
	global_load_lds_dwordx4 v[214:215], off
	v_lshl_add_u64 v[214:215], s[18:19], 0, v[132:133]
	s_add_i32 m0, s29, 0xe000
	s_nop 0
	global_load_lds_dwordx4 v[214:215], off
	s_waitcnt vmcnt(8)
	s_waitcnt lgkmcnt(0)
	s_setprio 1
	s_barrier
	v_mfma_f32_16x16x32_bf16 v[124:127], v[140:143], v[172:175], v[124:127]
	v_mfma_f32_16x16x32_bf16 v[120:123], v[148:151], v[172:175], v[120:123]
	v_mfma_f32_16x16x32_bf16 v[116:119], v[140:143], v[190:193], v[116:119]
	v_mfma_f32_16x16x32_bf16 v[108:111], v[148:151], v[190:193], v[108:111]
	v_mfma_f32_16x16x32_bf16 v[100:103], v[140:143], v[198:201], v[100:103]
	v_mfma_f32_16x16x32_bf16 v[92:95], v[148:151], v[198:201], v[92:95]
	v_mfma_f32_16x16x32_bf16 v[84:87], v[140:143], v[206:209], v[84:87]
	v_mfma_f32_16x16x32_bf16 v[76:79], v[148:151], v[206:209], v[76:79]
	v_mfma_f32_16x16x32_bf16 v[124:127], v[144:147], v[186:189], v[124:127]
	v_mfma_f32_16x16x32_bf16 v[120:123], v[152:155], v[186:189], v[120:123]
	v_mfma_f32_16x16x32_bf16 v[116:119], v[144:147], v[194:197], v[116:119]
	v_mfma_f32_16x16x32_bf16 v[108:111], v[152:155], v[194:197], v[108:111]
	v_mfma_f32_16x16x32_bf16 v[100:103], v[144:147], v[202:205], v[100:103]
	v_mfma_f32_16x16x32_bf16 v[92:95], v[152:155], v[202:205], v[92:95]
	v_mfma_f32_16x16x32_bf16 v[84:87], v[144:147], v[210:213], v[84:87]
	v_mfma_f32_16x16x32_bf16 v[76:79], v[152:155], v[210:213], v[76:79]
	s_setprio 0
	s_setprio 1
	v_mfma_f32_16x16x32_bf16 v[112:115], v[156:159], v[172:175], v[112:115]
	v_mfma_f32_16x16x32_bf16 v[104:107], v[164:167], v[172:175], v[104:107]
	v_mfma_f32_16x16x32_bf16 v[96:99], v[156:159], v[190:193], v[96:99]
	v_mfma_f32_16x16x32_bf16 v[88:91], v[164:167], v[190:193], v[88:91]
	v_mfma_f32_16x16x32_bf16 v[80:83], v[156:159], v[198:201], v[80:83]
	v_mfma_f32_16x16x32_bf16 v[72:75], v[164:167], v[198:201], v[72:75]
	v_mfma_f32_16x16x32_bf16 v[68:71], v[156:159], v[206:209], v[68:71]
	v_mfma_f32_16x16x32_bf16 v[64:67], v[164:167], v[206:209], v[64:67]
	v_mfma_f32_16x16x32_bf16 v[112:115], v[160:163], v[186:189], v[112:115]
	v_mfma_f32_16x16x32_bf16 v[104:107], v[168:171], v[186:189], v[104:107]
	v_mfma_f32_16x16x32_bf16 v[96:99], v[160:163], v[194:197], v[96:99]
	v_mfma_f32_16x16x32_bf16 v[88:91], v[168:171], v[194:197], v[88:91]
	v_mfma_f32_16x16x32_bf16 v[80:83], v[160:163], v[202:205], v[80:83]
	v_mfma_f32_16x16x32_bf16 v[72:75], v[168:171], v[202:205], v[72:75]
	v_mfma_f32_16x16x32_bf16 v[68:71], v[160:163], v[210:213], v[68:71]
	v_mfma_f32_16x16x32_bf16 v[64:67], v[168:171], v[210:213], v[64:67]
	s_barrier
	s_setprio 0
	s_add_i32 s45, s45, s28
	v_lshl_add_u64 v[214:215], s[20:21], 0, v[130:131]
	s_mov_b32 m0, s45
	ds_read_b128 v[172:175], v138 offset:16384
	ds_read_b128 v[186:189], v138 offset:17408
	ds_read_b128 v[190:193], v138 offset:18432
	ds_read_b128 v[194:197], v138 offset:19456
	ds_read_b128 v[198:201], v138 offset:20480
	ds_read_b128 v[202:205], v138 offset:21504
	ds_read_b128 v[206:209], v138 offset:22528
	ds_read_b128 v[210:213], v138 offset:23552
	global_load_lds_dwordx4 v[214:215], off
	s_add_i32 m0, s45, 0x2000
	s_add_u32 s46, s20, 0x80000
	v_lshl_add_u64 v[216:217], s[20:21], 0, v[128:129]
	s_addc_u32 s47, s21, 0
	s_add_i32 s45, s48, s28
	global_load_lds_dwordx4 v[216:217], off
	v_lshl_add_u64 v[218:219], s[46:47], 0, v[130:131]
	s_mov_b32 m0, s45
	v_lshl_add_u64 v[228:229], s[22:23], 0, v[128:129]
	global_load_lds_dwordx4 v[218:219], off
	v_lshl_add_u64 v[218:219], s[46:47], 0, v[128:129]
	s_add_i32 m0, s45, 0x2000
	s_nop 0
	global_load_lds_dwordx4 v[218:219], off
	v_lshl_add_u64 v[218:219], s[22:23], 0, v[130:131]
	s_mov_b32 m0, s29
	s_nop 0
	global_load_lds_dwordx4 v[218:219], off
	s_mov_b32 m0, s30
	s_nop 0
	global_load_lds_dwordx4 v[228:229], off
	s_waitcnt vmcnt(8)
	s_waitcnt lgkmcnt(0)
	s_setprio 1
	s_barrier
	v_mfma_f32_16x16x32_bf16 v[60:63], v[140:143], v[172:175], v[60:63]
	v_mfma_f32_16x16x32_bf16 v[56:59], v[148:151], v[172:175], v[56:59]
	v_mfma_f32_16x16x32_bf16 v[52:55], v[140:143], v[190:193], v[52:55]
	v_mfma_f32_16x16x32_bf16 v[44:47], v[148:151], v[190:193], v[44:47]
	v_mfma_f32_16x16x32_bf16 v[36:39], v[140:143], v[198:201], v[36:39]
	v_mfma_f32_16x16x32_bf16 v[28:31], v[148:151], v[198:201], v[28:31]
	v_mfma_f32_16x16x32_bf16 v[20:23], v[140:143], v[206:209], v[20:23]
	v_mfma_f32_16x16x32_bf16 v[12:15], v[148:151], v[206:209], v[12:15]
	v_mfma_f32_16x16x32_bf16 v[60:63], v[144:147], v[186:189], v[60:63]
	v_mfma_f32_16x16x32_bf16 v[56:59], v[152:155], v[186:189], v[56:59]
	v_mfma_f32_16x16x32_bf16 v[52:55], v[144:147], v[194:197], v[52:55]
	v_mfma_f32_16x16x32_bf16 v[44:47], v[152:155], v[194:197], v[44:47]
	v_mfma_f32_16x16x32_bf16 v[36:39], v[144:147], v[202:205], v[36:39]
	v_mfma_f32_16x16x32_bf16 v[28:31], v[152:155], v[202:205], v[28:31]
	v_mfma_f32_16x16x32_bf16 v[20:23], v[144:147], v[210:213], v[20:23]
	v_mfma_f32_16x16x32_bf16 v[12:15], v[152:155], v[210:213], v[12:15]
	s_setprio 0
	s_setprio 1
	v_mfma_f32_16x16x32_bf16 v[48:51], v[156:159], v[172:175], v[48:51]
	v_mfma_f32_16x16x32_bf16 v[40:43], v[164:167], v[172:175], v[40:43]
	v_mfma_f32_16x16x32_bf16 v[32:35], v[156:159], v[190:193], v[32:35]
	v_mfma_f32_16x16x32_bf16 v[24:27], v[164:167], v[190:193], v[24:27]
	v_mfma_f32_16x16x32_bf16 v[16:19], v[156:159], v[198:201], v[16:19]
	v_mfma_f32_16x16x32_bf16 v[8:11], v[164:167], v[198:201], v[8:11]
	v_mfma_f32_16x16x32_bf16 v[4:7], v[156:159], v[206:209], v[4:7]
	v_mfma_f32_16x16x32_bf16 v[0:3], v[164:167], v[206:209], v[0:3]
	v_mfma_f32_16x16x32_bf16 v[48:51], v[160:163], v[186:189], v[48:51]
	v_mfma_f32_16x16x32_bf16 v[40:43], v[168:171], v[186:189], v[40:43]
	v_mfma_f32_16x16x32_bf16 v[32:35], v[160:163], v[194:197], v[32:35]
	v_mfma_f32_16x16x32_bf16 v[24:27], v[168:171], v[194:197], v[24:27]
	v_mfma_f32_16x16x32_bf16 v[16:19], v[160:163], v[202:205], v[16:19]
	v_mfma_f32_16x16x32_bf16 v[8:11], v[168:171], v[202:205], v[8:11]
	v_mfma_f32_16x16x32_bf16 v[4:7], v[160:163], v[210:213], v[4:7]
	v_mfma_f32_16x16x32_bf16 v[0:3], v[168:171], v[210:213], v[0:3]
	s_barrier
	s_setprio 0
	s_add_i32 s45, 0, 0x18000
	v_add_u32_e32 v139, s45, v137
	s_add_i32 s46, 0, 0x1c000
	ds_read_b128 v[140:143], v139
	ds_read_b128 v[144:147], v139 offset:1024
	ds_read_b128 v[148:151], v139 offset:2048
	ds_read_b128 v[152:155], v139 offset:3072
	v_add_u32_e32 v139, s46, v137
	ds_read_b128 v[156:159], v139
	ds_read_b128 v[160:163], v139 offset:1024
	ds_read_b128 v[164:167], v139 offset:2048
	ds_read_b128 v[168:171], v139 offset:3072
	s_add_u32 s22, s22, 0x80000
	s_addc_u32 s23, s23, 0
	s_mov_b32 m0, s31
	v_lshl_add_u64 v[230:231], s[22:23], 0, v[130:131]
	ds_read_b128 v[172:175], v138 offset:32768
	ds_read_b128 v[186:189], v138 offset:33792
	ds_read_b128 v[190:193], v138 offset:34816
	ds_read_b128 v[194:197], v138 offset:35840
	ds_read_b128 v[198:201], v138 offset:36864
	ds_read_b128 v[202:205], v138 offset:37888
	ds_read_b128 v[206:209], v138 offset:38912
	ds_read_b128 v[210:213], v138 offset:39936
	global_load_lds_dwordx4 v[230:231], off
	v_lshl_add_u64 v[230:231], s[22:23], 0, v[128:129]
	s_mov_b32 m0, s34
	s_nop 0
	global_load_lds_dwordx4 v[230:231], off
	s_waitcnt vmcnt(8)
	s_waitcnt lgkmcnt(0)
	s_setprio 1
	s_barrier
	v_mfma_f32_16x16x32_bf16 v[124:127], v[140:143], v[172:175], v[124:127]
	v_mfma_f32_16x16x32_bf16 v[120:123], v[148:151], v[172:175], v[120:123]
	v_mfma_f32_16x16x32_bf16 v[116:119], v[140:143], v[190:193], v[116:119]
	v_mfma_f32_16x16x32_bf16 v[108:111], v[148:151], v[190:193], v[108:111]
	v_mfma_f32_16x16x32_bf16 v[100:103], v[140:143], v[198:201], v[100:103]
	v_mfma_f32_16x16x32_bf16 v[92:95], v[148:151], v[198:201], v[92:95]
	v_mfma_f32_16x16x32_bf16 v[84:87], v[140:143], v[206:209], v[84:87]
	v_mfma_f32_16x16x32_bf16 v[76:79], v[148:151], v[206:209], v[76:79]
	v_mfma_f32_16x16x32_bf16 v[124:127], v[144:147], v[186:189], v[124:127]
	v_mfma_f32_16x16x32_bf16 v[120:123], v[152:155], v[186:189], v[120:123]
	v_mfma_f32_16x16x32_bf16 v[116:119], v[144:147], v[194:197], v[116:119]
	v_mfma_f32_16x16x32_bf16 v[108:111], v[152:155], v[194:197], v[108:111]
	v_mfma_f32_16x16x32_bf16 v[100:103], v[144:147], v[202:205], v[100:103]
	v_mfma_f32_16x16x32_bf16 v[92:95], v[152:155], v[202:205], v[92:95]
	v_mfma_f32_16x16x32_bf16 v[84:87], v[144:147], v[210:213], v[84:87]
	v_mfma_f32_16x16x32_bf16 v[76:79], v[152:155], v[210:213], v[76:79]
	s_setprio 0
	s_setprio 1
	v_mfma_f32_16x16x32_bf16 v[112:115], v[156:159], v[172:175], v[112:115]
	v_mfma_f32_16x16x32_bf16 v[104:107], v[164:167], v[172:175], v[104:107]
	v_mfma_f32_16x16x32_bf16 v[96:99], v[156:159], v[190:193], v[96:99]
	v_mfma_f32_16x16x32_bf16 v[88:91], v[164:167], v[190:193], v[88:91]
	v_mfma_f32_16x16x32_bf16 v[80:83], v[156:159], v[198:201], v[80:83]
	v_mfma_f32_16x16x32_bf16 v[72:75], v[164:167], v[198:201], v[72:75]
	v_mfma_f32_16x16x32_bf16 v[68:71], v[156:159], v[206:209], v[68:71]
	v_mfma_f32_16x16x32_bf16 v[64:67], v[164:167], v[206:209], v[64:67]
	v_mfma_f32_16x16x32_bf16 v[112:115], v[160:163], v[186:189], v[112:115]
	v_mfma_f32_16x16x32_bf16 v[104:107], v[168:171], v[186:189], v[104:107]
	v_mfma_f32_16x16x32_bf16 v[96:99], v[160:163], v[194:197], v[96:99]
	v_mfma_f32_16x16x32_bf16 v[88:91], v[168:171], v[194:197], v[88:91]
	v_mfma_f32_16x16x32_bf16 v[80:83], v[160:163], v[202:205], v[80:83]
	v_mfma_f32_16x16x32_bf16 v[72:75], v[168:171], v[202:205], v[72:75]
	v_mfma_f32_16x16x32_bf16 v[68:71], v[160:163], v[210:213], v[68:71]
	v_mfma_f32_16x16x32_bf16 v[64:67], v[168:171], v[210:213], v[64:67]
	s_barrier
	s_setprio 0
	s_add_i32 s22, s45, s28
	v_lshl_add_u64 v[214:215], v[214:215], 0, s[0:1]
	s_mov_b32 m0, s22
	ds_read_b128 v[172:175], v138 offset:49152
	ds_read_b128 v[186:189], v138 offset:50176
	ds_read_b128 v[190:193], v138 offset:51200
	ds_read_b128 v[194:197], v138 offset:52224
	ds_read_b128 v[198:201], v138 offset:53248
	ds_read_b128 v[202:205], v138 offset:54272
	ds_read_b128 v[206:209], v138 offset:55296
	ds_read_b128 v[210:213], v138 offset:56320
	global_load_lds_dwordx4 v[214:215], off
	s_add_i32 m0, s22, 0x2000
	s_add_u32 s20, s20, 0x80080
	v_lshl_add_u64 v[214:215], v[216:217], 0, s[0:1]
	s_addc_u32 s21, s21, 0
	s_add_i32 s22, s46, s28
	global_load_lds_dwordx4 v[214:215], off
	v_lshl_add_u64 v[214:215], s[20:21], 0, v[130:131]
	s_mov_b32 m0, s22
	s_nop 0
	global_load_lds_dwordx4 v[214:215], off
	v_lshl_add_u64 v[214:215], s[20:21], 0, v[128:129]
	s_add_i32 m0, s22, 0x2000
	s_nop 0
	global_load_lds_dwordx4 v[214:215], off
	v_lshl_add_u64 v[214:215], v[218:219], 0, s[0:1]
	s_mov_b32 m0, s35
	s_nop 0
	global_load_lds_dwordx4 v[214:215], off
	v_lshl_add_u64 v[214:215], v[228:229], 0, s[0:1]
	s_mov_b32 m0, s36
	s_nop 0
	global_load_lds_dwordx4 v[214:215], off
	s_waitcnt vmcnt(8)
	s_waitcnt lgkmcnt(0)
	s_setprio 1
	s_barrier
	v_mfma_f32_16x16x32_bf16 v[60:63], v[140:143], v[172:175], v[60:63]
	v_mfma_f32_16x16x32_bf16 v[56:59], v[148:151], v[172:175], v[56:59]
	v_mfma_f32_16x16x32_bf16 v[52:55], v[140:143], v[190:193], v[52:55]
	v_mfma_f32_16x16x32_bf16 v[44:47], v[148:151], v[190:193], v[44:47]
	v_mfma_f32_16x16x32_bf16 v[36:39], v[140:143], v[198:201], v[36:39]
	v_mfma_f32_16x16x32_bf16 v[28:31], v[148:151], v[198:201], v[28:31]
	v_mfma_f32_16x16x32_bf16 v[20:23], v[140:143], v[206:209], v[20:23]
	v_mfma_f32_16x16x32_bf16 v[12:15], v[148:151], v[206:209], v[12:15]
	v_mfma_f32_16x16x32_bf16 v[60:63], v[144:147], v[186:189], v[60:63]
	v_mfma_f32_16x16x32_bf16 v[56:59], v[152:155], v[186:189], v[56:59]
	v_mfma_f32_16x16x32_bf16 v[52:55], v[144:147], v[194:197], v[52:55]
	v_mfma_f32_16x16x32_bf16 v[44:47], v[152:155], v[194:197], v[44:47]
	v_mfma_f32_16x16x32_bf16 v[36:39], v[144:147], v[202:205], v[36:39]
	v_mfma_f32_16x16x32_bf16 v[28:31], v[152:155], v[202:205], v[28:31]
	v_mfma_f32_16x16x32_bf16 v[20:23], v[144:147], v[210:213], v[20:23]
	v_mfma_f32_16x16x32_bf16 v[12:15], v[152:155], v[210:213], v[12:15]
	s_setprio 0
	s_setprio 1
	v_mfma_f32_16x16x32_bf16 v[48:51], v[156:159], v[172:175], v[48:51]
	v_mfma_f32_16x16x32_bf16 v[40:43], v[164:167], v[172:175], v[40:43]
	v_mfma_f32_16x16x32_bf16 v[32:35], v[156:159], v[190:193], v[32:35]
	v_mfma_f32_16x16x32_bf16 v[24:27], v[164:167], v[190:193], v[24:27]
	v_mfma_f32_16x16x32_bf16 v[16:19], v[156:159], v[198:201], v[16:19]
	v_mfma_f32_16x16x32_bf16 v[8:11], v[164:167], v[198:201], v[8:11]
	v_mfma_f32_16x16x32_bf16 v[4:7], v[156:159], v[206:209], v[4:7]
	v_mfma_f32_16x16x32_bf16 v[0:3], v[164:167], v[206:209], v[0:3]
	v_mfma_f32_16x16x32_bf16 v[48:51], v[160:163], v[186:189], v[48:51]
	v_mfma_f32_16x16x32_bf16 v[40:43], v[168:171], v[186:189], v[40:43]
	v_mfma_f32_16x16x32_bf16 v[32:35], v[160:163], v[194:197], v[32:35]
	v_mfma_f32_16x16x32_bf16 v[24:27], v[168:171], v[194:197], v[24:27]
	v_mfma_f32_16x16x32_bf16 v[16:19], v[160:163], v[202:205], v[16:19]
	v_mfma_f32_16x16x32_bf16 v[8:11], v[168:171], v[202:205], v[8:11]
	v_mfma_f32_16x16x32_bf16 v[4:7], v[160:163], v[210:213], v[4:7]
	v_mfma_f32_16x16x32_bf16 v[0:3], v[168:171], v[210:213], v[0:3]
	s_barrier
	s_setprio 0
	s_add_i32 s44, s44, 2
	s_add_u32 s42, s42, 0x100
	s_addc_u32 s43, s43, 0
	s_add_u32 s18, s18, 0x100
	s_addc_u32 s19, s19, 0
	s_cmp_gt_u32 s44, 29
	s_cbranch_scc0 .LBB0_474
	s_and_b64 vcc, exec, s[6:7]
	s_movk_i32 s22, 0x1000
	s_cbranch_vccz .LBB0_477
	s_barrier

.LBB0_490:
	s_add_u32 s28, s6, 0xfff80080
	s_addc_u32 s29, s7, -1
	s_add_i32 s52, 0, 0x10000
	s_cmp_eq_u32 s51, 28
	s_cselect_b32 s31, s23, s29
	s_cselect_b32 s30, s47, s28
	s_cselect_b32 s29, s21, s50
	s_cselect_b32 s28, s48, s49
	s_add_i32 s54, 0, 0x14000
	v_add_u32_e32 v140, s52, v187
	s_waitcnt lgkmcnt(0)
	v_add_u32_e32 v168, s54, v187
	ds_read_b128 v[128:131], v140
	ds_read_b128 v[132:135], v140 offset:1024
	ds_read_b128 v[136:139], v140 offset:2048
	ds_read_b128 v[140:143], v140 offset:3072
	ds_read_b128 v[156:159], v168
	ds_read_b128 v[160:163], v168 offset:1024
	ds_read_b128 v[164:167], v168 offset:2048
	ds_read_b128 v[168:171], v168 offset:3072
	v_lshl_add_u64 v[172:173], s[6:7], 0, v[154:155]
	s_add_i32 m0, s39, 0xc000
	ds_read_b128 v[190:193], v189
	ds_read_b128 v[194:197], v189 offset:1024
	ds_read_b128 v[198:201], v189 offset:2048
	ds_read_b128 v[202:205], v189 offset:3072
	ds_read_b128 v[206:209], v189 offset:4096
	ds_read_b128 v[210:213], v189 offset:5120
	ds_read_b128 v[214:217], v189 offset:6144
	ds_read_b128 v[236:239], v189 offset:7168
	global_load_lds_dwordx4 v[172:173], off
	v_lshl_add_u64 v[172:173], s[6:7], 0, v[152:153]
	s_add_i32 m0, s39, 0xe000
	s_nop 0
	global_load_lds_dwordx4 v[172:173], off
	s_waitcnt vmcnt(8)
	s_waitcnt lgkmcnt(0)
	s_setprio 1
	s_barrier
	v_mfma_f32_16x16x32_bf16 v[124:127], v[128:131], v[190:193], v[124:127]
	v_mfma_f32_16x16x32_bf16 v[120:123], v[136:139], v[190:193], v[120:123]
	v_mfma_f32_16x16x32_bf16 v[108:111], v[128:131], v[198:201], v[108:111]
	v_mfma_f32_16x16x32_bf16 v[104:107], v[136:139], v[198:201], v[104:107]
	v_mfma_f32_16x16x32_bf16 v[92:95], v[128:131], v[206:209], v[92:95]
	v_mfma_f32_16x16x32_bf16 v[88:91], v[136:139], v[206:209], v[88:91]
	v_mfma_f32_16x16x32_bf16 v[76:79], v[128:131], v[214:217], v[76:79]
	v_mfma_f32_16x16x32_bf16 v[72:75], v[136:139], v[214:217], v[72:75]
	v_mfma_f32_16x16x32_bf16 v[124:127], v[132:135], v[194:197], v[124:127]
	v_mfma_f32_16x16x32_bf16 v[120:123], v[140:143], v[194:197], v[120:123]
	v_mfma_f32_16x16x32_bf16 v[108:111], v[132:135], v[202:205], v[108:111]
	v_mfma_f32_16x16x32_bf16 v[104:107], v[140:143], v[202:205], v[104:107]
	v_mfma_f32_16x16x32_bf16 v[92:95], v[132:135], v[210:213], v[92:95]
	v_mfma_f32_16x16x32_bf16 v[88:91], v[140:143], v[210:213], v[88:91]
	v_mfma_f32_16x16x32_bf16 v[76:79], v[132:135], v[236:239], v[76:79]
	v_mfma_f32_16x16x32_bf16 v[72:75], v[140:143], v[236:239], v[72:75]
	s_setprio 0
	s_setprio 1
	v_mfma_f32_16x16x32_bf16 v[116:119], v[156:159], v[190:193], v[116:119]
	v_mfma_f32_16x16x32_bf16 v[112:115], v[164:167], v[190:193], v[112:115]
	v_mfma_f32_16x16x32_bf16 v[100:103], v[156:159], v[198:201], v[100:103]
	v_mfma_f32_16x16x32_bf16 v[96:99], v[164:167], v[198:201], v[96:99]
	v_mfma_f32_16x16x32_bf16 v[84:87], v[156:159], v[206:209], v[84:87]
	v_mfma_f32_16x16x32_bf16 v[80:83], v[164:167], v[206:209], v[80:83]
	v_mfma_f32_16x16x32_bf16 v[68:71], v[156:159], v[214:217], v[68:71]
	v_mfma_f32_16x16x32_bf16 v[64:67], v[164:167], v[214:217], v[64:67]
	v_mfma_f32_16x16x32_bf16 v[116:119], v[160:163], v[194:197], v[116:119]
	v_mfma_f32_16x16x32_bf16 v[112:115], v[168:171], v[194:197], v[112:115]
	v_mfma_f32_16x16x32_bf16 v[100:103], v[160:163], v[202:205], v[100:103]
	v_mfma_f32_16x16x32_bf16 v[96:99], v[168:171], v[202:205], v[96:99]
	v_mfma_f32_16x16x32_bf16 v[84:87], v[160:163], v[210:213], v[84:87]
	v_mfma_f32_16x16x32_bf16 v[80:83], v[168:171], v[210:213], v[80:83]
	v_mfma_f32_16x16x32_bf16 v[68:71], v[160:163], v[236:239], v[68:71]
	v_mfma_f32_16x16x32_bf16 v[64:67], v[168:171], v[236:239], v[64:67]
	s_barrier
	s_setprio 0
	s_add_i32 s52, s52, s38
	v_lshl_add_u64 v[172:173], s[28:29], 0, v[146:147]
	s_mov_b32 m0, s52
	ds_read_b128 v[190:193], v189 offset:16384
	ds_read_b128 v[194:197], v189 offset:17408
	ds_read_b128 v[198:201], v189 offset:18432
	ds_read_b128 v[202:205], v189 offset:19456
	ds_read_b128 v[206:209], v189 offset:20480
	ds_read_b128 v[210:213], v189 offset:21504
	ds_read_b128 v[214:217], v189 offset:22528
	ds_read_b128 v[236:239], v189 offset:23552
	global_load_lds_dwordx4 v[172:173], off
	s_add_i32 m0, s52, 0x2000
	s_add_u32 s52, s28, 0x80000
	v_lshl_add_u64 v[218:219], s[28:29], 0, v[144:145]
	s_addc_u32 s53, s29, 0
	s_add_i32 s54, s54, s38
	global_load_lds_dwordx4 v[218:219], off
	v_lshl_add_u64 v[228:229], s[52:53], 0, v[146:147]
	s_mov_b32 m0, s54
	v_lshl_add_u64 v[230:231], s[30:31], 0, v[144:145]
	global_load_lds_dwordx4 v[228:229], off
	v_lshl_add_u64 v[228:229], s[52:53], 0, v[144:145]
	s_add_i32 m0, s54, 0x2000
	s_nop 0
	global_load_lds_dwordx4 v[228:229], off
	v_lshl_add_u64 v[228:229], s[30:31], 0, v[146:147]
	s_mov_b32 m0, s39
	s_nop 0
	global_load_lds_dwordx4 v[228:229], off
	s_mov_b32 m0, s40
	s_nop 0
	global_load_lds_dwordx4 v[230:231], off
	s_waitcnt vmcnt(8)
	s_waitcnt lgkmcnt(0)
	s_setprio 1
	s_barrier
	v_mfma_f32_16x16x32_bf16 v[60:63], v[128:131], v[190:193], v[60:63]
	v_mfma_f32_16x16x32_bf16 v[56:59], v[136:139], v[190:193], v[56:59]
	v_mfma_f32_16x16x32_bf16 v[44:47], v[128:131], v[198:201], v[44:47]
	v_mfma_f32_16x16x32_bf16 v[40:43], v[136:139], v[198:201], v[40:43]
	v_mfma_f32_16x16x32_bf16 v[28:31], v[128:131], v[206:209], v[28:31]
	v_mfma_f32_16x16x32_bf16 v[24:27], v[136:139], v[206:209], v[24:27]
	v_mfma_f32_16x16x32_bf16 v[12:15], v[128:131], v[214:217], v[12:15]
	v_mfma_f32_16x16x32_bf16 v[8:11], v[136:139], v[214:217], v[8:11]
	v_mfma_f32_16x16x32_bf16 v[60:63], v[132:135], v[194:197], v[60:63]
	v_mfma_f32_16x16x32_bf16 v[56:59], v[140:143], v[194:197], v[56:59]
	v_mfma_f32_16x16x32_bf16 v[44:47], v[132:135], v[202:205], v[44:47]
	v_mfma_f32_16x16x32_bf16 v[40:43], v[140:143], v[202:205], v[40:43]
	v_mfma_f32_16x16x32_bf16 v[28:31], v[132:135], v[210:213], v[28:31]
	v_mfma_f32_16x16x32_bf16 v[24:27], v[140:143], v[210:213], v[24:27]
	v_mfma_f32_16x16x32_bf16 v[12:15], v[132:135], v[236:239], v[12:15]
	v_mfma_f32_16x16x32_bf16 v[8:11], v[140:143], v[236:239], v[8:11]
	s_setprio 0
	s_setprio 1
	v_mfma_f32_16x16x32_bf16 v[52:55], v[156:159], v[190:193], v[52:55]
	v_mfma_f32_16x16x32_bf16 v[48:51], v[164:167], v[190:193], v[48:51]
	v_mfma_f32_16x16x32_bf16 v[36:39], v[156:159], v[198:201], v[36:39]
	v_mfma_f32_16x16x32_bf16 v[32:35], v[164:167], v[198:201], v[32:35]
	v_mfma_f32_16x16x32_bf16 v[20:23], v[156:159], v[206:209], v[20:23]
	v_mfma_f32_16x16x32_bf16 v[16:19], v[164:167], v[206:209], v[16:19]
	v_mfma_f32_16x16x32_bf16 v[4:7], v[156:159], v[214:217], v[4:7]
	v_mfma_f32_16x16x32_bf16 v[0:3], v[164:167], v[214:217], v[0:3]
	v_mfma_f32_16x16x32_bf16 v[52:55], v[160:163], v[194:197], v[52:55]
	v_mfma_f32_16x16x32_bf16 v[48:51], v[168:171], v[194:197], v[48:51]
	v_mfma_f32_16x16x32_bf16 v[36:39], v[160:163], v[202:205], v[36:39]
	v_mfma_f32_16x16x32_bf16 v[32:35], v[168:171], v[202:205], v[32:35]
	v_mfma_f32_16x16x32_bf16 v[20:23], v[160:163], v[210:213], v[20:23]
	v_mfma_f32_16x16x32_bf16 v[16:19], v[168:171], v[210:213], v[16:19]
	v_mfma_f32_16x16x32_bf16 v[4:7], v[160:163], v[236:239], v[4:7]
	v_mfma_f32_16x16x32_bf16 v[0:3], v[168:171], v[236:239], v[0:3]
	s_barrier
	s_setprio 0
	s_add_i32 s52, 0, 0x18000
	s_add_i32 s53, 0, 0x1c000
	v_add_u32_e32 v140, s52, v187
	v_add_u32_e32 v168, s53, v187
	ds_read_b128 v[128:131], v140
	ds_read_b128 v[132:135], v140 offset:1024
	ds_read_b128 v[136:139], v140 offset:2048
	ds_read_b128 v[140:143], v140 offset:3072
	ds_read_b128 v[156:159], v168
	ds_read_b128 v[160:163], v168 offset:1024
	ds_read_b128 v[164:167], v168 offset:2048
	ds_read_b128 v[168:171], v168 offset:3072
	s_add_u32 s30, s30, 0x80000
	s_addc_u32 s31, s31, 0
	s_mov_b32 m0, s41
	v_lshl_add_u64 v[240:241], s[30:31], 0, v[146:147]
	ds_read_b128 v[190:193], v189 offset:32768
	ds_read_b128 v[194:197], v189 offset:33792
	ds_read_b128 v[198:201], v189 offset:34816
	ds_read_b128 v[202:205], v189 offset:35840
	ds_read_b128 v[206:209], v189 offset:36864
	ds_read_b128 v[210:213], v189 offset:37888
	ds_read_b128 v[214:217], v189 offset:38912
	ds_read_b128 v[236:239], v189 offset:39936
	global_load_lds_dwordx4 v[240:241], off
	v_lshl_add_u64 v[240:241], s[30:31], 0, v[144:145]
	s_mov_b32 m0, s42
	s_nop 0
	global_load_lds_dwordx4 v[240:241], off
	s_waitcnt vmcnt(8)
	s_waitcnt lgkmcnt(0)
	s_setprio 1
	s_barrier
	v_mfma_f32_16x16x32_bf16 v[124:127], v[128:131], v[190:193], v[124:127]
	v_mfma_f32_16x16x32_bf16 v[120:123], v[136:139], v[190:193], v[120:123]
	v_mfma_f32_16x16x32_bf16 v[108:111], v[128:131], v[198:201], v[108:111]
	v_mfma_f32_16x16x32_bf16 v[104:107], v[136:139], v[198:201], v[104:107]
	v_mfma_f32_16x16x32_bf16 v[92:95], v[128:131], v[206:209], v[92:95]
	v_mfma_f32_16x16x32_bf16 v[88:91], v[136:139], v[206:209], v[88:91]
	v_mfma_f32_16x16x32_bf16 v[76:79], v[128:131], v[214:217], v[76:79]
	v_mfma_f32_16x16x32_bf16 v[72:75], v[136:139], v[214:217], v[72:75]
	v_mfma_f32_16x16x32_bf16 v[124:127], v[132:135], v[194:197], v[124:127]
	v_mfma_f32_16x16x32_bf16 v[120:123], v[140:143], v[194:197], v[120:123]
	v_mfma_f32_16x16x32_bf16 v[108:111], v[132:135], v[202:205], v[108:111]
	v_mfma_f32_16x16x32_bf16 v[104:107], v[140:143], v[202:205], v[104:107]
	v_mfma_f32_16x16x32_bf16 v[92:95], v[132:135], v[210:213], v[92:95]
	v_mfma_f32_16x16x32_bf16 v[88:91], v[140:143], v[210:213], v[88:91]
	v_mfma_f32_16x16x32_bf16 v[76:79], v[132:135], v[236:239], v[76:79]
	v_mfma_f32_16x16x32_bf16 v[72:75], v[140:143], v[236:239], v[72:75]
	s_setprio 0
	s_setprio 1
	v_mfma_f32_16x16x32_bf16 v[116:119], v[156:159], v[190:193], v[116:119]
	v_mfma_f32_16x16x32_bf16 v[112:115], v[164:167], v[190:193], v[112:115]
	v_mfma_f32_16x16x32_bf16 v[100:103], v[156:159], v[198:201], v[100:103]
	v_mfma_f32_16x16x32_bf16 v[96:99], v[164:167], v[198:201], v[96:99]
	v_mfma_f32_16x16x32_bf16 v[84:87], v[156:159], v[206:209], v[84:87]
	v_mfma_f32_16x16x32_bf16 v[80:83], v[164:167], v[206:209], v[80:83]
	v_mfma_f32_16x16x32_bf16 v[68:71], v[156:159], v[214:217], v[68:71]
	v_mfma_f32_16x16x32_bf16 v[64:67], v[164:167], v[214:217], v[64:67]
	v_mfma_f32_16x16x32_bf16 v[116:119], v[160:163], v[194:197], v[116:119]
	v_mfma_f32_16x16x32_bf16 v[112:115], v[168:171], v[194:197], v[112:115]
	v_mfma_f32_16x16x32_bf16 v[100:103], v[160:163], v[202:205], v[100:103]
	v_mfma_f32_16x16x32_bf16 v[96:99], v[168:171], v[202:205], v[96:99]
	v_mfma_f32_16x16x32_bf16 v[84:87], v[160:163], v[210:213], v[84:87]
	v_mfma_f32_16x16x32_bf16 v[80:83], v[168:171], v[210:213], v[80:83]
	v_mfma_f32_16x16x32_bf16 v[68:71], v[160:163], v[236:239], v[68:71]
	v_mfma_f32_16x16x32_bf16 v[64:67], v[168:171], v[236:239], v[64:67]
	s_barrier
	s_setprio 0
	s_add_i32 s30, s52, s38
	v_lshl_add_u64 v[172:173], v[172:173], 0, s[0:1]
	s_mov_b32 m0, s30
	ds_read_b128 v[190:193], v189 offset:49152
	ds_read_b128 v[194:197], v189 offset:50176
	ds_read_b128 v[198:201], v189 offset:51200
	ds_read_b128 v[202:205], v189 offset:52224
	ds_read_b128 v[206:209], v189 offset:53248
	ds_read_b128 v[210:213], v189 offset:54272
	ds_read_b128 v[214:217], v189 offset:55296
	ds_read_b128 v[236:239], v189 offset:56320
	global_load_lds_dwordx4 v[172:173], off
	s_add_i32 m0, s30, 0x2000
	s_add_u32 s28, s28, 0x80080
	v_lshl_add_u64 v[172:173], v[218:219], 0, s[0:1]
	s_addc_u32 s29, s29, 0
	s_add_i32 s30, s53, s38
	global_load_lds_dwordx4 v[172:173], off
	v_lshl_add_u64 v[172:173], s[28:29], 0, v[146:147]
	s_mov_b32 m0, s30
	s_nop 0
	global_load_lds_dwordx4 v[172:173], off
	v_lshl_add_u64 v[172:173], s[28:29], 0, v[144:145]
	s_add_i32 m0, s30, 0x2000
	s_nop 0
	global_load_lds_dwordx4 v[172:173], off
	v_lshl_add_u64 v[172:173], v[228:229], 0, s[0:1]
	s_mov_b32 m0, s44
	s_nop 0
	global_load_lds_dwordx4 v[172:173], off
	v_lshl_add_u64 v[172:173], v[230:231], 0, s[0:1]
	s_mov_b32 m0, s45
	s_nop 0
	global_load_lds_dwordx4 v[172:173], off
	s_waitcnt vmcnt(8)
	s_waitcnt lgkmcnt(0)
	s_setprio 1
	s_barrier
	v_mfma_f32_16x16x32_bf16 v[60:63], v[128:131], v[190:193], v[60:63]
	v_mfma_f32_16x16x32_bf16 v[56:59], v[136:139], v[190:193], v[56:59]
	v_mfma_f32_16x16x32_bf16 v[44:47], v[128:131], v[198:201], v[44:47]
	v_mfma_f32_16x16x32_bf16 v[40:43], v[136:139], v[198:201], v[40:43]
	v_mfma_f32_16x16x32_bf16 v[28:31], v[128:131], v[206:209], v[28:31]
	v_mfma_f32_16x16x32_bf16 v[24:27], v[136:139], v[206:209], v[24:27]
	v_mfma_f32_16x16x32_bf16 v[12:15], v[128:131], v[214:217], v[12:15]
	v_mfma_f32_16x16x32_bf16 v[8:11], v[136:139], v[214:217], v[8:11]
	v_mfma_f32_16x16x32_bf16 v[60:63], v[132:135], v[194:197], v[60:63]
	v_mfma_f32_16x16x32_bf16 v[56:59], v[140:143], v[194:197], v[56:59]
	v_mfma_f32_16x16x32_bf16 v[44:47], v[132:135], v[202:205], v[44:47]
	v_mfma_f32_16x16x32_bf16 v[40:43], v[140:143], v[202:205], v[40:43]
	v_mfma_f32_16x16x32_bf16 v[28:31], v[132:135], v[210:213], v[28:31]
	v_mfma_f32_16x16x32_bf16 v[24:27], v[140:143], v[210:213], v[24:27]
	v_mfma_f32_16x16x32_bf16 v[12:15], v[132:135], v[236:239], v[12:15]
	v_mfma_f32_16x16x32_bf16 v[8:11], v[140:143], v[236:239], v[8:11]
	s_setprio 0
	s_setprio 1
	v_mfma_f32_16x16x32_bf16 v[52:55], v[156:159], v[190:193], v[52:55]
	v_mfma_f32_16x16x32_bf16 v[48:51], v[164:167], v[190:193], v[48:51]
	v_mfma_f32_16x16x32_bf16 v[36:39], v[156:159], v[198:201], v[36:39]
	v_mfma_f32_16x16x32_bf16 v[32:35], v[164:167], v[198:201], v[32:35]
	v_mfma_f32_16x16x32_bf16 v[20:23], v[156:159], v[206:209], v[20:23]
	v_mfma_f32_16x16x32_bf16 v[16:19], v[164:167], v[206:209], v[16:19]
	v_mfma_f32_16x16x32_bf16 v[4:7], v[156:159], v[214:217], v[4:7]
	v_mfma_f32_16x16x32_bf16 v[0:3], v[164:167], v[214:217], v[0:3]
	v_mfma_f32_16x16x32_bf16 v[52:55], v[160:163], v[194:197], v[52:55]
	v_mfma_f32_16x16x32_bf16 v[48:51], v[168:171], v[194:197], v[48:51]
	v_mfma_f32_16x16x32_bf16 v[36:39], v[160:163], v[202:205], v[36:39]
	v_mfma_f32_16x16x32_bf16 v[32:35], v[168:171], v[202:205], v[32:35]
	v_mfma_f32_16x16x32_bf16 v[20:23], v[160:163], v[210:213], v[20:23]
	v_mfma_f32_16x16x32_bf16 v[16:19], v[168:171], v[210:213], v[16:19]
	v_mfma_f32_16x16x32_bf16 v[4:7], v[160:163], v[236:239], v[4:7]
	v_mfma_f32_16x16x32_bf16 v[0:3], v[168:171], v[236:239], v[0:3]
	s_barrier
	s_setprio 0
	s_add_i32 s51, s51, 2
	s_add_u32 s49, s49, 0x100
	s_addc_u32 s50, s50, 0
	s_add_u32 s6, s6, 0x100
	s_addc_u32 s7, s7, 0
	s_cmp_gt_u32 s51, 29
	s_cbranch_scc0 .LBB0_490
	s_and_b64 vcc, exec, s[12:13]
	s_cbranch_vccz .LBB0_493
	s_barrier
